# first K-iteration of every tile peeled with SrcC=0 on each accumulator's first MFMA; the 128 per-tile v_mov zero-inits deleted
# baseline (speedup 1.0000x reference)
; #define PG8_STAGE(bufoff, gbase, voff) do { _Pragma("unroll") for (int _i = 0; _i < 2; ++_i) \
;         __builtin_amdgcn_global_load_lds((const unsigned*)((const char*)(gbase) + (voff)[_i]), (PG8_LAS unsigned*)(lds + (bufoff) + ldsw + _i * 8192), 16, 0, 0); } while (0)
; #define PG8_LDA(dst, b, h) do { _Pragma("unroll") for (int m = 0; m < 4; ++m) _Pragma("unroll") for (int k = 0; k < 2; ++k) dst[m][k] = *(const PG8_LAS bf16x8*)(lds + PG8_SA(b, h) + aoff + m * 2048 + k * 1024); } while (0)
; #define PG8_LDB(dst, b, h) do { _Pragma("unroll") for (int n = 0; n < 2; ++n) _Pragma("unroll") for (int k = 0; k < 2; ++k) dst[n][k] = *(const PG8_LAS bf16x8*)(lds + PG8_SB(b, h) + boff + n * 2048 + k * 1024); } while (0)
; #define PG8_WAIT_V(n) asm volatile("s_waitcnt vmcnt(" #n ")" ::: "memory")
; #define PG8_BAR __builtin_amdgcn_s_barrier()
; template <class Epi, class Sched, bool ALIGN_EPI = false, bool SP2 = false>
; __device__ __forceinline__ void gemm_phase(PG8_LAS unsigned char* lds, const Gemm g, const Sched& S, const Epi& E) {
;     ...
;         const bool has_next = S.next(ui + 1, nxt);
;         const char* nA = has_next ? (const char*)g.A + (size_t)nxt.pm * tstep : cA; const char* nB = has_next ? (const char*)g.Bt + (size_t)nxt.pn * tstep : cB;
;         for (int t = 0; t < nt; t += 2) {
;             const bool last = (t == nt - 2);
;             const char* a1 = cA + (size_t)(t + 1) * kstep;
;             const char* a2 = last ? nA : cA + (size_t)(t + 2) * kstep; const char* b2 = last ? nB : cB + (size_t)(t + 2) * kstep;
;             const char* a3 = a2 + kstep; const char* b3 = b2 + kstep;
;             if (last && has_next) S.a_ready(nxt);
;             if constexpr (SP2) {
;             PG8_LDB(B0, 0, 0); PG8_LDB(B1, 0, 1); PG8_SCHED; PG8_LDA(At, 0, 0); PG8_STAGE(PG8_SA(1, 1), a1 + hstep, voffA);
;             PG8_WAIT_V(8); PG8_WAIT_L(0); PG8_BAR; PG8_MMA(0, 0, At, B0); PG8_MMA(0, 1, At, B1); PG8_BAR; PG8_SCHED;
;             PG8_LDA(At, 0, 1); PG8_STAGE(PG8_SB(0, 0), b2, voffB); PG8_STAGE(PG8_SB(0, 1), b2 + hstep, voffB); PG8_STAGE(PG8_SA(0, 0), a2, voffA);
;     ...
;         for (int a = 0; a < 2; ++a)
; #pragma unroll
;             for (int b = 0; b < 2; ++b)
; #pragma unroll
;                 for (int m = 0; m < 4; ++m)
; #pragma unroll
;                     for (int n = 0; n < 2; ++n) acc[a][b][m][n] = (f32x4){0.f, 0.f, 0.f, 0.f};
.LBB0_179:
	s_ashr_i32 s25, s24, 31
	s_lshl_b64 s[26:27], s[24:25], 21
	s_add_u32 s26, s84, s26
	s_addc_u32 s27, s85, s27
	s_and_b64 s[28:29], s[4:5], exec
	s_cselect_b32 s7, s27, s35
	s_cselect_b32 s25, s26, s34
	s_ashr_i32 s15, s14, 31
	s_lshl_b64 s[28:29], s[14:15], 21
	s_add_u32 s28, s78, s28
	s_addc_u32 s29, s79, s29
	s_and_b64 s[38:39], s[4:5], exec
	s_cselect_b32 s15, s29, s37
	s_cselect_b32 s31, s28, s36
	s_add_u32 s34, s34, 0x100080
	s_addc_u32 s35, s35, 0
	s_add_u32 s54, s36, 0x100
	s_addc_u32 s55, s37, 0
	s_mov_b32 s56, -2
	s_add_u32 s36, s34, 0xfff00000
	s_addc_u32 s37, s35, -1
	s_mov_b32 m0, s45
	s_nop 0
	global_load_lds_dwordx4 v138, s[36:37]
	s_mov_b32 m0, s46
	s_nop 0
	global_load_lds_dwordx4 v142, s[36:37]
	s_add_u32 s36, s36, 0x80
	s_addc_u32 s37, s37, 0
	ds_read_b128 v[130:133], v170
	ds_read_b128 v[134:137], v170 offset:1024
	ds_read_b128 v[178:181], v170 offset:2048
	ds_read_b128 v[182:185], v170 offset:3072
	ds_read_b128 v[186:189], v171
	ds_read_b128 v[190:193], v171 offset:1024
	ds_read_b128 v[194:197], v171 offset:2048
	ds_read_b128 v[200:203], v171 offset:3072
	s_cmp_eq_u32 s56, 60
	s_cselect_b32 s39, s7, s37
	s_cselect_b32 s38, s25, s36
	s_cselect_b32 s37, s15, s55
	s_cselect_b32 s36, s31, s54
	s_add_i32 m0, s40, 0xc000
	ds_read_b128 v[204:207], v172
	ds_read_b128 v[208:211], v172 offset:1024
	ds_read_b128 v[212:215], v172 offset:2048
	ds_read_b128 v[216:219], v172 offset:3072
	ds_read_b128 v[220:223], v172 offset:4096
	ds_read_b128 v[224:227], v172 offset:5120
	ds_read_b128 v[228:231], v172 offset:6144
	ds_read_b128 v[232:235], v172 offset:7168
	global_load_lds_dwordx4 v148, s[34:35]
	s_add_i32 m0, s40, 0xe000
	s_nop 0
	global_load_lds_dwordx4 v150, s[34:35]
	s_waitcnt vmcnt(8)
	s_waitcnt lgkmcnt(0)
	s_setprio 1
	s_barrier
	v_mfma_f32_16x16x32_bf16 v[126:129], v[130:133], v[204:207], 0
	v_mfma_f32_16x16x32_bf16 v[122:125], v[178:181], v[204:207], 0
	v_mfma_f32_16x16x32_bf16 v[110:113], v[130:133], v[212:215], 0
	v_mfma_f32_16x16x32_bf16 v[106:109], v[178:181], v[212:215], 0
	v_mfma_f32_16x16x32_bf16 v[94:97], v[130:133], v[220:223], 0
	v_mfma_f32_16x16x32_bf16 v[90:93], v[178:181], v[220:223], 0
	v_mfma_f32_16x16x32_bf16 v[78:81], v[130:133], v[228:231], 0
	v_mfma_f32_16x16x32_bf16 v[74:77], v[178:181], v[228:231], 0
	v_mfma_f32_16x16x32_bf16 v[126:129], v[134:137], v[208:211], v[126:129]
	v_mfma_f32_16x16x32_bf16 v[122:125], v[182:185], v[208:211], v[122:125]
	v_mfma_f32_16x16x32_bf16 v[110:113], v[134:137], v[216:219], v[110:113]
	v_mfma_f32_16x16x32_bf16 v[106:109], v[182:185], v[216:219], v[106:109]
	v_mfma_f32_16x16x32_bf16 v[94:97], v[134:137], v[224:227], v[94:97]
	v_mfma_f32_16x16x32_bf16 v[90:93], v[182:185], v[224:227], v[90:93]
	v_mfma_f32_16x16x32_bf16 v[78:81], v[134:137], v[232:235], v[78:81]
	v_mfma_f32_16x16x32_bf16 v[74:77], v[182:185], v[232:235], v[74:77]
	v_mfma_f32_16x16x32_bf16 v[118:121], v[186:189], v[204:207], 0
	v_mfma_f32_16x16x32_bf16 v[114:117], v[194:197], v[204:207], 0
	v_mfma_f32_16x16x32_bf16 v[102:105], v[186:189], v[212:215], 0
	v_mfma_f32_16x16x32_bf16 v[98:101], v[194:197], v[212:215], 0
	v_mfma_f32_16x16x32_bf16 v[86:89], v[186:189], v[220:223], 0
	v_mfma_f32_16x16x32_bf16 v[82:85], v[194:197], v[220:223], 0
	v_mfma_f32_16x16x32_bf16 v[70:73], v[186:189], v[228:231], 0
	v_mfma_f32_16x16x32_bf16 v[66:69], v[194:197], v[228:231], 0
	v_mfma_f32_16x16x32_bf16 v[118:121], v[190:193], v[208:211], v[118:121]
	v_mfma_f32_16x16x32_bf16 v[114:117], v[200:203], v[208:211], v[114:117]
	v_mfma_f32_16x16x32_bf16 v[102:105], v[190:193], v[216:219], v[102:105]
	v_mfma_f32_16x16x32_bf16 v[98:101], v[200:203], v[216:219], v[98:101]
	v_mfma_f32_16x16x32_bf16 v[86:89], v[190:193], v[224:227], v[86:89]
	v_mfma_f32_16x16x32_bf16 v[82:85], v[200:203], v[224:227], v[82:85]
	v_mfma_f32_16x16x32_bf16 v[70:73], v[190:193], v[232:235], v[70:73]
	v_mfma_f32_16x16x32_bf16 v[66:69], v[200:203], v[232:235], v[66:69]
	s_barrier
	s_setprio 0
	s_add_i32 s57, s49, s33
	s_mov_b32 m0, s57
	ds_read_b128 v[204:207], v172 offset:16384
	ds_read_b128 v[208:211], v172 offset:17408
	ds_read_b128 v[212:215], v172 offset:18432
	ds_read_b128 v[216:219], v172 offset:19456
	ds_read_b128 v[220:223], v172 offset:20480
	ds_read_b128 v[224:227], v172 offset:21504
	ds_read_b128 v[228:231], v172 offset:22528
	ds_read_b128 v[232:235], v172 offset:23552
	global_load_lds_dwordx4 v140, s[36:37]
	s_add_i32 m0, s57, 0x2000
	s_add_u32 s58, s36, 0x100000
	s_addc_u32 s59, s37, 0
	s_add_i32 s57, s50, s33
	global_load_lds_dwordx4 v144, s[36:37]
	s_mov_b32 m0, s57
	s_nop 0
	global_load_lds_dwordx4 v140, s[58:59]
	s_add_i32 m0, s57, 0x2000
	s_nop 0
	global_load_lds_dwordx4 v144, s[58:59]
	s_waitcnt vmcnt(6)
	s_waitcnt lgkmcnt(0)
	s_setprio 1
	s_barrier
; #define PG8_STAGE(bufoff, gbase, voff) do { _Pragma("unroll") for (int _i = 0; _i < 2; ++_i) \
;         __builtin_amdgcn_global_load_lds((const unsigned*)((const char*)(gbase) + (voff)[_i]), (PG8_LAS unsigned*)(lds + (bufoff) + ldsw + _i * 8192), 16, 0, 0); } while (0)
; #define PG8_LDA(dst, b, h) do { _Pragma("unroll") for (int m = 0; m < 4; ++m) _Pragma("unroll") for (int k = 0; k < 2; ++k) dst[m][k] = *(const PG8_LAS bf16x8*)(lds + PG8_SA(b, h) + aoff + m * 2048 + k * 1024); } while (0)
; #define PG8_LDB(dst, b, h) do { _Pragma("unroll") for (int n = 0; n < 2; ++n) _Pragma("unroll") for (int k = 0; k < 2; ++k) dst[n][k] = *(const PG8_LAS bf16x8*)(lds + PG8_SB(b, h) + boff + n * 2048 + k * 1024); } while (0)
; #define PG8_MMA(ai, bj, At, Bt) do { __builtin_amdgcn_s_setprio(1); _Pragma("unroll") for (int m = 0; m < 4; ++m) _Pragma("unroll") for (int n = 0; n < 2; ++n) _Pragma("unroll") for (int k = 0; k < 2; ++k) \
;         acc[ai][bj][m][n] = __builtin_amdgcn_mfma_f32_16x16x32_bf16(Bt[n][k], At[m][k], acc[ai][bj][m][n], 0, 0, 0); __builtin_amdgcn_s_setprio(0); } while (0)
; #define PG8_WAIT_V(n) asm volatile("s_waitcnt vmcnt(" #n ")" ::: "memory")
; #define PG8_WAIT_L(n) asm volatile("s_waitcnt lgkmcnt(" #n ")" ::: "memory")
; #define PG8_BAR __builtin_amdgcn_s_barrier()
; #define PG8_SCHED __builtin_amdgcn_sched_barrier(0)
; template <class Epi, class Sched, bool ALIGN_EPI = false, bool SP2 = false>
; __device__ __forceinline__ void gemm_phase(PG8_LAS unsigned char* lds, const Gemm g, const Sched& S, const Epi& E) {
;     ...
;             PG8_WAIT_V(8); PG8_WAIT_L(0); PG8_BAR; PG8_MMA(1, 0, At, B0); PG8_MMA(1, 1, At, B1); PG8_BAR; PG8_SCHED;
;             PG8_LDB(B0, 1, 0); PG8_LDB(B1, 1, 1); PG8_SCHED; PG8_LDA(At, 1, 0); PG8_STAGE(PG8_SA(0, 1), a2 + hstep, voffA);
;             PG8_WAIT_V(8); PG8_WAIT_L(0); PG8_BAR; PG8_MMA(0, 0, At, B0); PG8_MMA(0, 1, At, B1); PG8_BAR; PG8_SCHED;
	v_mfma_f32_16x16x32_bf16 v[62:65], v[130:133], v[204:207], 0
	v_mfma_f32_16x16x32_bf16 v[58:61], v[178:181], v[204:207], 0
	v_mfma_f32_16x16x32_bf16 v[46:49], v[130:133], v[212:215], 0
	v_mfma_f32_16x16x32_bf16 v[42:45], v[178:181], v[212:215], 0
	v_mfma_f32_16x16x32_bf16 v[30:33], v[130:133], v[220:223], 0
	v_mfma_f32_16x16x32_bf16 v[26:29], v[178:181], v[220:223], 0
	v_mfma_f32_16x16x32_bf16 v[14:17], v[130:133], v[228:231], 0
	v_mfma_f32_16x16x32_bf16 v[10:13], v[178:181], v[228:231], 0
	v_mfma_f32_16x16x32_bf16 v[62:65], v[134:137], v[208:211], v[62:65]
	v_mfma_f32_16x16x32_bf16 v[58:61], v[182:185], v[208:211], v[58:61]
	v_mfma_f32_16x16x32_bf16 v[46:49], v[134:137], v[216:219], v[46:49]
	v_mfma_f32_16x16x32_bf16 v[42:45], v[182:185], v[216:219], v[42:45]
	v_mfma_f32_16x16x32_bf16 v[30:33], v[134:137], v[224:227], v[30:33]
	v_mfma_f32_16x16x32_bf16 v[26:29], v[182:185], v[224:227], v[26:29]
	v_mfma_f32_16x16x32_bf16 v[14:17], v[134:137], v[232:235], v[14:17]
	v_mfma_f32_16x16x32_bf16 v[10:13], v[182:185], v[232:235], v[10:13]
	v_mfma_f32_16x16x32_bf16 v[54:57], v[186:189], v[204:207], 0
	v_mfma_f32_16x16x32_bf16 v[50:53], v[194:197], v[204:207], 0
	v_mfma_f32_16x16x32_bf16 v[38:41], v[186:189], v[212:215], 0
	v_mfma_f32_16x16x32_bf16 v[34:37], v[194:197], v[212:215], 0
	v_mfma_f32_16x16x32_bf16 v[22:25], v[186:189], v[220:223], 0
	v_mfma_f32_16x16x32_bf16 v[18:21], v[194:197], v[220:223], 0
	v_mfma_f32_16x16x32_bf16 v[6:9], v[186:189], v[228:231], 0
	v_mfma_f32_16x16x32_bf16 v[2:5], v[194:197], v[228:231], 0
	v_mfma_f32_16x16x32_bf16 v[54:57], v[190:193], v[208:211], v[54:57]
	v_mfma_f32_16x16x32_bf16 v[50:53], v[200:203], v[208:211], v[50:53]
	v_mfma_f32_16x16x32_bf16 v[38:41], v[190:193], v[216:219], v[38:41]
	v_mfma_f32_16x16x32_bf16 v[34:37], v[200:203], v[216:219], v[34:37]
	v_mfma_f32_16x16x32_bf16 v[22:25], v[190:193], v[224:227], v[22:25]
	v_mfma_f32_16x16x32_bf16 v[18:21], v[200:203], v[224:227], v[18:21]
	v_mfma_f32_16x16x32_bf16 v[6:9], v[190:193], v[232:235], v[6:9]
	v_mfma_f32_16x16x32_bf16 v[2:5], v[200:203], v[232:235], v[2:5]
	s_barrier
	s_setprio 0
	s_mov_b32 m0, s40
	s_nop 0
	global_load_lds_dwordx4 v138, s[38:39]
	s_mov_b32 m0, s41
	s_nop 0
	global_load_lds_dwordx4 v142, s[38:39]
	s_add_i32 s57, 0, 0x18000
	v_add_u32_e32 v146, s57, v159
	s_add_i32 s58, 0, 0x1c000
	ds_read_b128 v[130:133], v146
	ds_read_b128 v[134:137], v146 offset:1024
	ds_read_b128 v[178:181], v146 offset:2048
	ds_read_b128 v[182:185], v146 offset:3072
	v_add_u32_e32 v146, s58, v159
	ds_read_b128 v[186:189], v146
	ds_read_b128 v[190:193], v146 offset:1024
	ds_read_b128 v[194:197], v146 offset:2048
	ds_read_b128 v[200:203], v146 offset:3072
	s_add_u32 s38, s38, 0x100000
	s_addc_u32 s39, s39, 0
	s_mov_b32 m0, s42
	ds_read_b128 v[204:207], v172 offset:32768
	ds_read_b128 v[208:211], v172 offset:33792
	ds_read_b128 v[212:215], v172 offset:34816
	ds_read_b128 v[216:219], v172 offset:35840
	ds_read_b128 v[220:223], v172 offset:36864
	ds_read_b128 v[224:227], v172 offset:37888
	ds_read_b128 v[228:231], v172 offset:38912
	ds_read_b128 v[232:235], v172 offset:39936
	global_load_lds_dwordx4 v138, s[38:39]
	s_mov_b32 m0, s43
	s_nop 0
	global_load_lds_dwordx4 v142, s[38:39]
	s_waitcnt vmcnt(8)
	s_waitcnt lgkmcnt(0)
	s_setprio 1
	s_barrier
; #define PG8_STAGE(bufoff, gbase, voff) do { _Pragma("unroll") for (int _i = 0; _i < 2; ++_i) \
;         __builtin_amdgcn_global_load_lds((const unsigned*)((const char*)(gbase) + (voff)[_i]), (PG8_LAS unsigned*)(lds + (bufoff) + ldsw + _i * 8192), 16, 0, 0); } while (0)
; #define PG8_LDA(dst, b, h) do { _Pragma("unroll") for (int m = 0; m < 4; ++m) _Pragma("unroll") for (int k = 0; k < 2; ++k) dst[m][k] = *(const PG8_LAS bf16x8*)(lds + PG8_SA(b, h) + aoff + m * 2048 + k * 1024); } while (0)
; #define PG8_MMA(ai, bj, At, Bt) do { __builtin_amdgcn_s_setprio(1); _Pragma("unroll") for (int m = 0; m < 4; ++m) _Pragma("unroll") for (int n = 0; n < 2; ++n) _Pragma("unroll") for (int k = 0; k < 2; ++k) \
;         acc[ai][bj][m][n] = __builtin_amdgcn_mfma_f32_16x16x32_bf16(Bt[n][k], At[m][k], acc[ai][bj][m][n], 0, 0, 0); __builtin_amdgcn_s_setprio(0); } while (0)
; #define PG8_WAIT_V(n) asm volatile("s_waitcnt vmcnt(" #n ")" ::: "memory")
; #define PG8_WAIT_L(n) asm volatile("s_waitcnt lgkmcnt(" #n ")" ::: "memory")
; #define PG8_BAR __builtin_amdgcn_s_barrier()
; #define PG8_SCHED __builtin_amdgcn_sched_barrier(0)
; template <class Epi, class Sched, bool ALIGN_EPI = false, bool SP2 = false>
; __device__ __forceinline__ void gemm_phase(PG8_LAS unsigned char* lds, const Gemm g, const Sched& S, const Epi& E) {
;     ...
;             PG8_WAIT_V(8); PG8_WAIT_L(0); PG8_BAR; PG8_MMA(0, 0, At, B0); PG8_MMA(0, 1, At, B1); PG8_BAR; PG8_SCHED;
;             PG8_LDA(At, 1, 1); PG8_STAGE(PG8_SB(1, 0), b3, voffB); PG8_STAGE(PG8_SB(1, 1), b3 + hstep, voffB); PG8_STAGE(PG8_SA(1, 0), a3, voffA);
;             PG8_WAIT_V(8); PG8_WAIT_L(0); PG8_BAR; PG8_MMA(1, 0, At, B0); PG8_MMA(1, 1, At, B1); PG8_BAR; PG8_SCHED;
	v_mfma_f32_16x16x32_bf16 v[126:129], v[130:133], v[204:207], v[126:129]
	v_mfma_f32_16x16x32_bf16 v[122:125], v[178:181], v[204:207], v[122:125]
	v_mfma_f32_16x16x32_bf16 v[110:113], v[130:133], v[212:215], v[110:113]
	v_mfma_f32_16x16x32_bf16 v[106:109], v[178:181], v[212:215], v[106:109]
	v_mfma_f32_16x16x32_bf16 v[94:97], v[130:133], v[220:223], v[94:97]
	v_mfma_f32_16x16x32_bf16 v[90:93], v[178:181], v[220:223], v[90:93]
	v_mfma_f32_16x16x32_bf16 v[78:81], v[130:133], v[228:231], v[78:81]
	v_mfma_f32_16x16x32_bf16 v[74:77], v[178:181], v[228:231], v[74:77]
	v_mfma_f32_16x16x32_bf16 v[126:129], v[134:137], v[208:211], v[126:129]
	v_mfma_f32_16x16x32_bf16 v[122:125], v[182:185], v[208:211], v[122:125]
	v_mfma_f32_16x16x32_bf16 v[110:113], v[134:137], v[216:219], v[110:113]
	v_mfma_f32_16x16x32_bf16 v[106:109], v[182:185], v[216:219], v[106:109]
	v_mfma_f32_16x16x32_bf16 v[94:97], v[134:137], v[224:227], v[94:97]
	v_mfma_f32_16x16x32_bf16 v[90:93], v[182:185], v[224:227], v[90:93]
	v_mfma_f32_16x16x32_bf16 v[78:81], v[134:137], v[232:235], v[78:81]
	v_mfma_f32_16x16x32_bf16 v[74:77], v[182:185], v[232:235], v[74:77]
	v_mfma_f32_16x16x32_bf16 v[118:121], v[186:189], v[204:207], v[118:121]
	v_mfma_f32_16x16x32_bf16 v[114:117], v[194:197], v[204:207], v[114:117]
	v_mfma_f32_16x16x32_bf16 v[102:105], v[186:189], v[212:215], v[102:105]
	v_mfma_f32_16x16x32_bf16 v[98:101], v[194:197], v[212:215], v[98:101]
	v_mfma_f32_16x16x32_bf16 v[86:89], v[186:189], v[220:223], v[86:89]
	v_mfma_f32_16x16x32_bf16 v[82:85], v[194:197], v[220:223], v[82:85]
	v_mfma_f32_16x16x32_bf16 v[70:73], v[186:189], v[228:231], v[70:73]
	v_mfma_f32_16x16x32_bf16 v[66:69], v[194:197], v[228:231], v[66:69]
	v_mfma_f32_16x16x32_bf16 v[118:121], v[190:193], v[208:211], v[118:121]
	v_mfma_f32_16x16x32_bf16 v[114:117], v[200:203], v[208:211], v[114:117]
	v_mfma_f32_16x16x32_bf16 v[102:105], v[190:193], v[216:219], v[102:105]
	v_mfma_f32_16x16x32_bf16 v[98:101], v[200:203], v[216:219], v[98:101]
	v_mfma_f32_16x16x32_bf16 v[86:89], v[190:193], v[224:227], v[86:89]
	v_mfma_f32_16x16x32_bf16 v[82:85], v[200:203], v[224:227], v[82:85]
	v_mfma_f32_16x16x32_bf16 v[70:73], v[190:193], v[232:235], v[70:73]
	v_mfma_f32_16x16x32_bf16 v[66:69], v[200:203], v[232:235], v[66:69]
	s_barrier
	s_setprio 0
	s_add_i32 s38, s57, s33
	s_add_u32 s36, s36, 0x80
	s_addc_u32 s37, s37, 0
	s_mov_b32 m0, s38
	ds_read_b128 v[204:207], v172 offset:49152
	ds_read_b128 v[208:211], v172 offset:50176
	ds_read_b128 v[212:215], v172 offset:51200
	ds_read_b128 v[216:219], v172 offset:52224
	ds_read_b128 v[220:223], v172 offset:53248
	ds_read_b128 v[224:227], v172 offset:54272
	ds_read_b128 v[228:231], v172 offset:55296
	ds_read_b128 v[232:235], v172 offset:56320
	global_load_lds_dwordx4 v140, s[36:37]
	s_add_i32 m0, s38, 0x2000
	s_add_i32 s38, s58, s33
	global_load_lds_dwordx4 v144, s[36:37]
	s_add_u32 s36, s36, 0x100000
	s_addc_u32 s37, s37, 0
	s_mov_b32 m0, s38
	s_nop 0
	global_load_lds_dwordx4 v140, s[36:37]
	s_add_i32 m0, s38, 0x2000
	s_nop 0
	global_load_lds_dwordx4 v144, s[36:37]
	s_waitcnt vmcnt(6)
	s_waitcnt lgkmcnt(0)
	s_setprio 1
	s_barrier
	v_mfma_f32_16x16x32_bf16 v[62:65], v[130:133], v[204:207], v[62:65]
	v_mfma_f32_16x16x32_bf16 v[58:61], v[178:181], v[204:207], v[58:61]
	v_mfma_f32_16x16x32_bf16 v[46:49], v[130:133], v[212:215], v[46:49]
	v_mfma_f32_16x16x32_bf16 v[42:45], v[178:181], v[212:215], v[42:45]
	v_mfma_f32_16x16x32_bf16 v[30:33], v[130:133], v[220:223], v[30:33]
	v_mfma_f32_16x16x32_bf16 v[26:29], v[178:181], v[220:223], v[26:29]
	v_mfma_f32_16x16x32_bf16 v[14:17], v[130:133], v[228:231], v[14:17]
	v_mfma_f32_16x16x32_bf16 v[10:13], v[178:181], v[228:231], v[10:13]
	v_mfma_f32_16x16x32_bf16 v[62:65], v[134:137], v[208:211], v[62:65]
	v_mfma_f32_16x16x32_bf16 v[58:61], v[182:185], v[208:211], v[58:61]
	v_mfma_f32_16x16x32_bf16 v[46:49], v[134:137], v[216:219], v[46:49]
	v_mfma_f32_16x16x32_bf16 v[42:45], v[182:185], v[216:219], v[42:45]
	v_mfma_f32_16x16x32_bf16 v[30:33], v[134:137], v[224:227], v[30:33]
	v_mfma_f32_16x16x32_bf16 v[26:29], v[182:185], v[224:227], v[26:29]
	v_mfma_f32_16x16x32_bf16 v[14:17], v[134:137], v[232:235], v[14:17]
	v_mfma_f32_16x16x32_bf16 v[10:13], v[182:185], v[232:235], v[10:13]
	v_mfma_f32_16x16x32_bf16 v[54:57], v[186:189], v[204:207], v[54:57]
	v_mfma_f32_16x16x32_bf16 v[50:53], v[194:197], v[204:207], v[50:53]
	v_mfma_f32_16x16x32_bf16 v[38:41], v[186:189], v[212:215], v[38:41]
	v_mfma_f32_16x16x32_bf16 v[34:37], v[194:197], v[212:215], v[34:37]
	v_mfma_f32_16x16x32_bf16 v[22:25], v[186:189], v[220:223], v[22:25]
	v_mfma_f32_16x16x32_bf16 v[18:21], v[194:197], v[220:223], v[18:21]
	v_mfma_f32_16x16x32_bf16 v[6:9], v[186:189], v[228:231], v[6:9]
	v_mfma_f32_16x16x32_bf16 v[2:5], v[194:197], v[228:231], v[2:5]
	v_mfma_f32_16x16x32_bf16 v[54:57], v[190:193], v[208:211], v[54:57]
	v_mfma_f32_16x16x32_bf16 v[50:53], v[200:203], v[208:211], v[50:53]
	v_mfma_f32_16x16x32_bf16 v[38:41], v[190:193], v[216:219], v[38:41]
	v_mfma_f32_16x16x32_bf16 v[34:37], v[200:203], v[216:219], v[34:37]
	v_mfma_f32_16x16x32_bf16 v[22:25], v[190:193], v[224:227], v[22:25]
	v_mfma_f32_16x16x32_bf16 v[18:21], v[200:203], v[224:227], v[18:21]
	v_mfma_f32_16x16x32_bf16 v[6:9], v[190:193], v[232:235], v[6:9]
	v_mfma_f32_16x16x32_bf16 v[2:5], v[200:203], v[232:235], v[2:5]
	s_barrier
	s_setprio 0
	s_add_i32 s56, s56, 2
	s_add_u32 s34, s34, 0x100
	s_addc_u32 s35, s35, 0
	s_add_u32 s54, s54, 0x100
	s_addc_u32 s55, s55, 0
	s_cmp_gt_u32 s56, 61
	.p2align 8

; #define PG8_STAGE(bufoff, gbase, voff) do { _Pragma("unroll") for (int _i = 0; _i < 2; ++_i) \
;         __builtin_amdgcn_global_load_lds((const unsigned*)((const char*)(gbase) + (voff)[_i]), (PG8_LAS unsigned*)(lds + (bufoff) + ldsw + _i * 8192), 16, 0, 0); } while (0)
; #define PG8_LDA(dst, b, h) do { _Pragma("unroll") for (int m = 0; m < 4; ++m) _Pragma("unroll") for (int k = 0; k < 2; ++k) dst[m][k] = *(const PG8_LAS bf16x8*)(lds + PG8_SA(b, h) + aoff + m * 2048 + k * 1024); } while (0)
; #define PG8_LDB(dst, b, h) do { _Pragma("unroll") for (int n = 0; n < 2; ++n) _Pragma("unroll") for (int k = 0; k < 2; ++k) dst[n][k] = *(const PG8_LAS bf16x8*)(lds + PG8_SB(b, h) + boff + n * 2048 + k * 1024); } while (0)
; #define PG8_WAIT_V(n) asm volatile("s_waitcnt vmcnt(" #n ")" ::: "memory")
; #define PG8_WAIT_L(n) asm volatile("s_waitcnt lgkmcnt(" #n ")" ::: "memory")
; #define PG8_BAR __builtin_amdgcn_s_barrier()
; #define PG8_SCHED __builtin_amdgcn_sched_barrier(0)
; template <class Epi, class Sched, bool ALIGN_EPI = false, bool SP2 = false>
; __device__ __forceinline__ void gemm_phase(PG8_LAS unsigned char* lds, const Gemm g, const Sched& S, const Epi& E) {
;     ...
;         const bool has_next = S.next(ui + 1, nxt);
;         const char* nA = has_next ? (const char*)g.A + (size_t)nxt.pm * tstep : cA; const char* nB = has_next ? (const char*)g.Bt + (size_t)nxt.pn * tstep : cB;
;         for (int t = 0; t < nt; t += 2) {
;             const bool last = (t == nt - 2);
;             const char* a1 = cA + (size_t)(t + 1) * kstep;
;             const char* a2 = last ? nA : cA + (size_t)(t + 2) * kstep; const char* b2 = last ? nB : cB + (size_t)(t + 2) * kstep;
;             const char* a3 = a2 + kstep; const char* b3 = b2 + kstep;
;             if (last && has_next) S.a_ready(nxt);
;             if constexpr (SP2) {
;             PG8_LDB(B0, 0, 0); PG8_LDB(B1, 0, 1); PG8_SCHED; PG8_LDA(At, 0, 0); PG8_STAGE(PG8_SA(1, 1), a1 + hstep, voffA);
;             PG8_WAIT_V(8); PG8_WAIT_L(0); PG8_BAR; PG8_MMA(0, 0, At, B0); PG8_MMA(0, 1, At, B1); PG8_BAR; PG8_SCHED;
;             PG8_LDA(At, 0, 1); PG8_STAGE(PG8_SB(0, 0), b2, voffB); PG8_STAGE(PG8_SB(0, 1), b2 + hstep, voffB); PG8_STAGE(PG8_SA(0, 0), a2, voffA);
;             PG8_WAIT_V(8); PG8_WAIT_L(0); PG8_BAR; PG8_MMA(1, 0, At, B0); PG8_MMA(1, 1, At, B1); PG8_BAR; PG8_SCHED;
.LBB0_856:
	s_ashr_i32 s15, s14, 31
	s_lshl_b64 s[24:25], s[14:15], 20
	s_add_u32 s24, s84, s24
	s_addc_u32 s25, s85, s25
	s_and_b64 s[26:27], s[0:1], exec
	s_cselect_b32 s15, s25, s31
	s_cselect_b32 s50, s24, s30
	s_ashr_i32 s13, s12, 31
	s_lshl_b64 s[26:27], s[12:13], 20
	s_add_u32 s26, s20, s26
	s_addc_u32 s27, s21, s27
	s_and_b64 s[36:37], s[0:1], exec
	s_cselect_b32 s13, s27, s35
	s_cselect_b32 s51, s26, s34
	s_add_u32 s30, s30, 0x80080
	s_addc_u32 s31, s31, 0
	s_add_u32 s52, s34, 0x100
	s_addc_u32 s53, s35, 0
	s_mov_b32 s56, -2
	s_add_u32 s34, s30, 0xfff80000
	s_addc_u32 s35, s31, -1
	s_mov_b32 m0, s43
	s_nop 0
	global_load_lds_dwordx4 v150, s[34:35]
	s_mov_b32 m0, s44
	s_nop 0
	global_load_lds_dwordx4 v154, s[34:35]
	s_add_u32 s34, s34, 0x80
	s_addc_u32 s35, s35, 0
	ds_read_b128 v[130:133], v180
	ds_read_b128 v[134:137], v180 offset:1024
	ds_read_b128 v[138:141], v180 offset:2048
	ds_read_b128 v[142:145], v180 offset:3072
	ds_read_b128 v[146:149], v181
	ds_read_b128 v[166:169], v181 offset:1024
	ds_read_b128 v[170:173], v181 offset:2048
	ds_read_b128 v[174:177], v181 offset:3072
	s_cmp_eq_u32 s56, 28
	s_cselect_b32 s37, s15, s35
	s_cselect_b32 s36, s50, s34
	s_cselect_b32 s35, s13, s53
	s_cselect_b32 s34, s51, s52
	s_add_i32 m0, s29, 0xc000
	ds_read_b128 v[184:187], v182
	ds_read_b128 v[188:191], v182 offset:1024
	ds_read_b128 v[192:195], v182 offset:2048
	ds_read_b128 v[200:203], v182 offset:3072
	ds_read_b128 v[204:207], v182 offset:4096
	ds_read_b128 v[208:211], v182 offset:5120
	ds_read_b128 v[212:215], v182 offset:6144
	ds_read_b128 v[216:219], v182 offset:7168
	global_load_lds_dwordx4 v158, s[30:31]
	s_add_i32 m0, s29, 0xe000
	s_nop 0
	global_load_lds_dwordx4 v160, s[30:31]
	s_waitcnt vmcnt(8)
	s_waitcnt lgkmcnt(0)
	s_setprio 1
	s_barrier
	v_mfma_f32_16x16x32_bf16 v[126:129], v[130:133], v[184:187], 0
	v_mfma_f32_16x16x32_bf16 v[122:125], v[138:141], v[184:187], 0
	v_mfma_f32_16x16x32_bf16 v[110:113], v[130:133], v[192:195], 0
	v_mfma_f32_16x16x32_bf16 v[106:109], v[138:141], v[192:195], 0
	v_mfma_f32_16x16x32_bf16 v[94:97], v[130:133], v[204:207], 0
	v_mfma_f32_16x16x32_bf16 v[90:93], v[138:141], v[204:207], 0
	v_mfma_f32_16x16x32_bf16 v[78:81], v[130:133], v[212:215], 0
	v_mfma_f32_16x16x32_bf16 v[74:77], v[138:141], v[212:215], 0
	v_mfma_f32_16x16x32_bf16 v[126:129], v[134:137], v[188:191], v[126:129]
	v_mfma_f32_16x16x32_bf16 v[122:125], v[142:145], v[188:191], v[122:125]
	v_mfma_f32_16x16x32_bf16 v[110:113], v[134:137], v[200:203], v[110:113]
	v_mfma_f32_16x16x32_bf16 v[106:109], v[142:145], v[200:203], v[106:109]
	v_mfma_f32_16x16x32_bf16 v[94:97], v[134:137], v[208:211], v[94:97]
	v_mfma_f32_16x16x32_bf16 v[90:93], v[142:145], v[208:211], v[90:93]
	v_mfma_f32_16x16x32_bf16 v[78:81], v[134:137], v[216:219], v[78:81]
	v_mfma_f32_16x16x32_bf16 v[74:77], v[142:145], v[216:219], v[74:77]
	v_mfma_f32_16x16x32_bf16 v[118:121], v[146:149], v[184:187], 0
	v_mfma_f32_16x16x32_bf16 v[114:117], v[170:173], v[184:187], 0
	v_mfma_f32_16x16x32_bf16 v[102:105], v[146:149], v[192:195], 0
	v_mfma_f32_16x16x32_bf16 v[98:101], v[170:173], v[192:195], 0
	v_mfma_f32_16x16x32_bf16 v[86:89], v[146:149], v[204:207], 0
	v_mfma_f32_16x16x32_bf16 v[82:85], v[170:173], v[204:207], 0
	v_mfma_f32_16x16x32_bf16 v[70:73], v[146:149], v[212:215], 0
	v_mfma_f32_16x16x32_bf16 v[66:69], v[170:173], v[212:215], 0
	v_mfma_f32_16x16x32_bf16 v[118:121], v[166:169], v[188:191], v[118:121]
	v_mfma_f32_16x16x32_bf16 v[114:117], v[174:177], v[188:191], v[114:117]
	v_mfma_f32_16x16x32_bf16 v[102:105], v[166:169], v[200:203], v[102:105]
	v_mfma_f32_16x16x32_bf16 v[98:101], v[174:177], v[200:203], v[98:101]
	v_mfma_f32_16x16x32_bf16 v[86:89], v[166:169], v[208:211], v[86:89]
	v_mfma_f32_16x16x32_bf16 v[82:85], v[174:177], v[208:211], v[82:85]
	v_mfma_f32_16x16x32_bf16 v[70:73], v[166:169], v[216:219], v[70:73]
	v_mfma_f32_16x16x32_bf16 v[66:69], v[174:177], v[216:219], v[66:69]
	s_barrier
	s_setprio 0
	s_add_i32 s57, s46, s38
	s_mov_b32 m0, s57
	ds_read_b128 v[184:187], v182 offset:16384
	ds_read_b128 v[188:191], v182 offset:17408
	ds_read_b128 v[192:195], v182 offset:18432
	ds_read_b128 v[200:203], v182 offset:19456
	ds_read_b128 v[204:207], v182 offset:20480
	ds_read_b128 v[208:211], v182 offset:21504
	ds_read_b128 v[212:215], v182 offset:22528
	ds_read_b128 v[216:219], v182 offset:23552
	global_load_lds_dwordx4 v152, s[34:35]
	s_add_i32 m0, s57, 0x2000
	s_add_u32 s58, s34, 0x80000
	s_addc_u32 s59, s35, 0
	s_add_i32 s57, s47, s38
	global_load_lds_dwordx4 v156, s[34:35]
	s_mov_b32 m0, s57
	s_nop 0
	global_load_lds_dwordx4 v152, s[58:59]
	s_add_i32 m0, s57, 0x2000
	s_nop 0
	global_load_lds_dwordx4 v156, s[58:59]
	s_waitcnt vmcnt(6)
	s_waitcnt lgkmcnt(0)
	s_setprio 1
	s_barrier
; #define PG8_STAGE(bufoff, gbase, voff) do { _Pragma("unroll") for (int _i = 0; _i < 2; ++_i) \
;         __builtin_amdgcn_global_load_lds((const unsigned*)((const char*)(gbase) + (voff)[_i]), (PG8_LAS unsigned*)(lds + (bufoff) + ldsw + _i * 8192), 16, 0, 0); } while (0)
; #define PG8_LDA(dst, b, h) do { _Pragma("unroll") for (int m = 0; m < 4; ++m) _Pragma("unroll") for (int k = 0; k < 2; ++k) dst[m][k] = *(const PG8_LAS bf16x8*)(lds + PG8_SA(b, h) + aoff + m * 2048 + k * 1024); } while (0)
; #define PG8_LDB(dst, b, h) do { _Pragma("unroll") for (int n = 0; n < 2; ++n) _Pragma("unroll") for (int k = 0; k < 2; ++k) dst[n][k] = *(const PG8_LAS bf16x8*)(lds + PG8_SB(b, h) + boff + n * 2048 + k * 1024); } while (0)
; #define PG8_MMA(ai, bj, At, Bt) do { __builtin_amdgcn_s_setprio(1); _Pragma("unroll") for (int m = 0; m < 4; ++m) _Pragma("unroll") for (int n = 0; n < 2; ++n) _Pragma("unroll") for (int k = 0; k < 2; ++k) \
;         acc[ai][bj][m][n] = __builtin_amdgcn_mfma_f32_16x16x32_bf16(Bt[n][k], At[m][k], acc[ai][bj][m][n], 0, 0, 0); __builtin_amdgcn_s_setprio(0); } while (0)
; #define PG8_WAIT_V(n) asm volatile("s_waitcnt vmcnt(" #n ")" ::: "memory")
; #define PG8_WAIT_L(n) asm volatile("s_waitcnt lgkmcnt(" #n ")" ::: "memory")
; #define PG8_BAR __builtin_amdgcn_s_barrier()
; #define PG8_SCHED __builtin_amdgcn_sched_barrier(0)
; template <class Epi, class Sched, bool ALIGN_EPI = false, bool SP2 = false>
; __device__ __forceinline__ void gemm_phase(PG8_LAS unsigned char* lds, const Gemm g, const Sched& S, const Epi& E) {
;     ...
;             PG8_WAIT_V(8); PG8_WAIT_L(0); PG8_BAR; PG8_MMA(0, 0, At, B0); PG8_MMA(0, 1, At, B1); PG8_BAR; PG8_SCHED;
;             PG8_LDA(At, 0, 1); PG8_STAGE(PG8_SB(0, 0), b2, voffB); PG8_STAGE(PG8_SB(0, 1), b2 + hstep, voffB); PG8_STAGE(PG8_SA(0, 0), a2, voffA);
;             PG8_WAIT_V(8); PG8_WAIT_L(0); PG8_BAR; PG8_MMA(1, 0, At, B0); PG8_MMA(1, 1, At, B1); PG8_BAR; PG8_SCHED;
;             PG8_LDB(B0, 1, 0); PG8_LDB(B1, 1, 1); PG8_SCHED; PG8_LDA(At, 1, 0); PG8_STAGE(PG8_SA(0, 1), a2 + hstep, voffA);
;             PG8_WAIT_V(8); PG8_WAIT_L(0); PG8_BAR; PG8_MMA(0, 0, At, B0); PG8_MMA(0, 1, At, B1); PG8_BAR; PG8_SCHED;
	v_mfma_f32_16x16x32_bf16 v[62:65], v[130:133], v[184:187], 0
	v_mfma_f32_16x16x32_bf16 v[58:61], v[138:141], v[184:187], 0
	v_mfma_f32_16x16x32_bf16 v[46:49], v[130:133], v[192:195], 0
	v_mfma_f32_16x16x32_bf16 v[42:45], v[138:141], v[192:195], 0
	v_mfma_f32_16x16x32_bf16 v[30:33], v[130:133], v[204:207], 0
	v_mfma_f32_16x16x32_bf16 v[26:29], v[138:141], v[204:207], 0
	v_mfma_f32_16x16x32_bf16 v[14:17], v[130:133], v[212:215], 0
	v_mfma_f32_16x16x32_bf16 v[10:13], v[138:141], v[212:215], 0
	v_mfma_f32_16x16x32_bf16 v[62:65], v[134:137], v[188:191], v[62:65]
	v_mfma_f32_16x16x32_bf16 v[58:61], v[142:145], v[188:191], v[58:61]
	v_mfma_f32_16x16x32_bf16 v[46:49], v[134:137], v[200:203], v[46:49]
	v_mfma_f32_16x16x32_bf16 v[42:45], v[142:145], v[200:203], v[42:45]
	v_mfma_f32_16x16x32_bf16 v[30:33], v[134:137], v[208:211], v[30:33]
	v_mfma_f32_16x16x32_bf16 v[26:29], v[142:145], v[208:211], v[26:29]
	v_mfma_f32_16x16x32_bf16 v[14:17], v[134:137], v[216:219], v[14:17]
	v_mfma_f32_16x16x32_bf16 v[10:13], v[142:145], v[216:219], v[10:13]
	v_mfma_f32_16x16x32_bf16 v[54:57], v[146:149], v[184:187], 0
	v_mfma_f32_16x16x32_bf16 v[50:53], v[170:173], v[184:187], 0
	v_mfma_f32_16x16x32_bf16 v[38:41], v[146:149], v[192:195], 0
	v_mfma_f32_16x16x32_bf16 v[34:37], v[170:173], v[192:195], 0
	v_mfma_f32_16x16x32_bf16 v[22:25], v[146:149], v[204:207], 0
	v_mfma_f32_16x16x32_bf16 v[18:21], v[170:173], v[204:207], 0
	v_mfma_f32_16x16x32_bf16 v[6:9], v[146:149], v[212:215], 0
	v_mfma_f32_16x16x32_bf16 v[2:5], v[170:173], v[212:215], 0
	v_mfma_f32_16x16x32_bf16 v[54:57], v[166:169], v[188:191], v[54:57]
	v_mfma_f32_16x16x32_bf16 v[50:53], v[174:177], v[188:191], v[50:53]
	v_mfma_f32_16x16x32_bf16 v[38:41], v[166:169], v[200:203], v[38:41]
	v_mfma_f32_16x16x32_bf16 v[34:37], v[174:177], v[200:203], v[34:37]
	v_mfma_f32_16x16x32_bf16 v[22:25], v[166:169], v[208:211], v[22:25]
	v_mfma_f32_16x16x32_bf16 v[18:21], v[174:177], v[208:211], v[18:21]
	v_mfma_f32_16x16x32_bf16 v[6:9], v[166:169], v[216:219], v[6:9]
	v_mfma_f32_16x16x32_bf16 v[2:5], v[174:177], v[216:219], v[2:5]
	s_barrier
	s_setprio 0
	s_mov_b32 m0, s29
	s_nop 0
	global_load_lds_dwordx4 v150, s[36:37]
	s_mov_b32 m0, s39
	s_nop 0
	global_load_lds_dwordx4 v154, s[36:37]
	s_add_i32 s57, 0, 0x18000
	s_add_i32 s58, 0, 0x1c000
	v_add_u32_e32 v142, s57, v178
	v_add_u32_e32 v174, s58, v178
	ds_read_b128 v[130:133], v142
	ds_read_b128 v[134:137], v142 offset:1024
	ds_read_b128 v[138:141], v142 offset:2048
	ds_read_b128 v[142:145], v142 offset:3072
	ds_read_b128 v[146:149], v174
	ds_read_b128 v[166:169], v174 offset:1024
	ds_read_b128 v[170:173], v174 offset:2048
	ds_read_b128 v[174:177], v174 offset:3072
	s_add_u32 s36, s36, 0x80000
	s_addc_u32 s37, s37, 0
	s_mov_b32 m0, s40
	ds_read_b128 v[184:187], v182 offset:32768
	ds_read_b128 v[188:191], v182 offset:33792
	ds_read_b128 v[192:195], v182 offset:34816
	ds_read_b128 v[200:203], v182 offset:35840
	ds_read_b128 v[204:207], v182 offset:36864
	ds_read_b128 v[208:211], v182 offset:37888
	ds_read_b128 v[212:215], v182 offset:38912
	ds_read_b128 v[216:219], v182 offset:39936
	global_load_lds_dwordx4 v150, s[36:37]
	s_mov_b32 m0, s41
	s_nop 0
	global_load_lds_dwordx4 v154, s[36:37]
	s_waitcnt vmcnt(8)
	s_waitcnt lgkmcnt(0)
	s_setprio 1
	s_barrier
; #define PG8_STAGE(bufoff, gbase, voff) do { _Pragma("unroll") for (int _i = 0; _i < 2; ++_i) \
;         __builtin_amdgcn_global_load_lds((const unsigned*)((const char*)(gbase) + (voff)[_i]), (PG8_LAS unsigned*)(lds + (bufoff) + ldsw + _i * 8192), 16, 0, 0); } while (0)
; #define PG8_LDA(dst, b, h) do { _Pragma("unroll") for (int m = 0; m < 4; ++m) _Pragma("unroll") for (int k = 0; k < 2; ++k) dst[m][k] = *(const PG8_LAS bf16x8*)(lds + PG8_SA(b, h) + aoff + m * 2048 + k * 1024); } while (0)
; #define PG8_MMA(ai, bj, At, Bt) do { __builtin_amdgcn_s_setprio(1); _Pragma("unroll") for (int m = 0; m < 4; ++m) _Pragma("unroll") for (int n = 0; n < 2; ++n) _Pragma("unroll") for (int k = 0; k < 2; ++k) \
;         acc[ai][bj][m][n] = __builtin_amdgcn_mfma_f32_16x16x32_bf16(Bt[n][k], At[m][k], acc[ai][bj][m][n], 0, 0, 0); __builtin_amdgcn_s_setprio(0); } while (0)
; #define PG8_WAIT_V(n) asm volatile("s_waitcnt vmcnt(" #n ")" ::: "memory")
; #define PG8_WAIT_L(n) asm volatile("s_waitcnt lgkmcnt(" #n ")" ::: "memory")
; #define PG8_BAR __builtin_amdgcn_s_barrier()
; #define PG8_SCHED __builtin_amdgcn_sched_barrier(0)
; template <class Epi, class Sched, bool ALIGN_EPI = false, bool SP2 = false>
; __device__ __forceinline__ void gemm_phase(PG8_LAS unsigned char* lds, const Gemm g, const Sched& S, const Epi& E) {
;     ...
;             PG8_WAIT_V(8); PG8_WAIT_L(0); PG8_BAR; PG8_MMA(0, 0, At, B0); PG8_MMA(0, 1, At, B1); PG8_BAR; PG8_SCHED;
;             PG8_LDA(At, 1, 1); PG8_STAGE(PG8_SB(1, 0), b3, voffB); PG8_STAGE(PG8_SB(1, 1), b3 + hstep, voffB); PG8_STAGE(PG8_SA(1, 0), a3, voffA);
;             PG8_WAIT_V(8); PG8_WAIT_L(0); PG8_BAR; PG8_MMA(1, 0, At, B0); PG8_MMA(1, 1, At, B1); PG8_BAR; PG8_SCHED;
	v_mfma_f32_16x16x32_bf16 v[126:129], v[130:133], v[184:187], v[126:129]
	v_mfma_f32_16x16x32_bf16 v[122:125], v[138:141], v[184:187], v[122:125]
	v_mfma_f32_16x16x32_bf16 v[110:113], v[130:133], v[192:195], v[110:113]
	v_mfma_f32_16x16x32_bf16 v[106:109], v[138:141], v[192:195], v[106:109]
	v_mfma_f32_16x16x32_bf16 v[94:97], v[130:133], v[204:207], v[94:97]
	v_mfma_f32_16x16x32_bf16 v[90:93], v[138:141], v[204:207], v[90:93]
	v_mfma_f32_16x16x32_bf16 v[78:81], v[130:133], v[212:215], v[78:81]
	v_mfma_f32_16x16x32_bf16 v[74:77], v[138:141], v[212:215], v[74:77]
	v_mfma_f32_16x16x32_bf16 v[126:129], v[134:137], v[188:191], v[126:129]
	v_mfma_f32_16x16x32_bf16 v[122:125], v[142:145], v[188:191], v[122:125]
	v_mfma_f32_16x16x32_bf16 v[110:113], v[134:137], v[200:203], v[110:113]
	v_mfma_f32_16x16x32_bf16 v[106:109], v[142:145], v[200:203], v[106:109]
	v_mfma_f32_16x16x32_bf16 v[94:97], v[134:137], v[208:211], v[94:97]
	v_mfma_f32_16x16x32_bf16 v[90:93], v[142:145], v[208:211], v[90:93]
	v_mfma_f32_16x16x32_bf16 v[78:81], v[134:137], v[216:219], v[78:81]
	v_mfma_f32_16x16x32_bf16 v[74:77], v[142:145], v[216:219], v[74:77]
	v_mfma_f32_16x16x32_bf16 v[118:121], v[146:149], v[184:187], v[118:121]
	v_mfma_f32_16x16x32_bf16 v[114:117], v[170:173], v[184:187], v[114:117]
	v_mfma_f32_16x16x32_bf16 v[102:105], v[146:149], v[192:195], v[102:105]
	v_mfma_f32_16x16x32_bf16 v[98:101], v[170:173], v[192:195], v[98:101]
	v_mfma_f32_16x16x32_bf16 v[86:89], v[146:149], v[204:207], v[86:89]
	v_mfma_f32_16x16x32_bf16 v[82:85], v[170:173], v[204:207], v[82:85]
	v_mfma_f32_16x16x32_bf16 v[70:73], v[146:149], v[212:215], v[70:73]
	v_mfma_f32_16x16x32_bf16 v[66:69], v[170:173], v[212:215], v[66:69]
	v_mfma_f32_16x16x32_bf16 v[118:121], v[166:169], v[188:191], v[118:121]
	v_mfma_f32_16x16x32_bf16 v[114:117], v[174:177], v[188:191], v[114:117]
	v_mfma_f32_16x16x32_bf16 v[102:105], v[166:169], v[200:203], v[102:105]
	v_mfma_f32_16x16x32_bf16 v[98:101], v[174:177], v[200:203], v[98:101]
	v_mfma_f32_16x16x32_bf16 v[86:89], v[166:169], v[208:211], v[86:89]
	v_mfma_f32_16x16x32_bf16 v[82:85], v[174:177], v[208:211], v[82:85]
	v_mfma_f32_16x16x32_bf16 v[70:73], v[166:169], v[216:219], v[70:73]
	v_mfma_f32_16x16x32_bf16 v[66:69], v[174:177], v[216:219], v[66:69]
	s_barrier
	s_setprio 0
	s_add_i32 s36, s57, s38
	s_add_u32 s34, s34, 0x80
	s_addc_u32 s35, s35, 0
	s_mov_b32 m0, s36
	ds_read_b128 v[184:187], v182 offset:49152
	ds_read_b128 v[188:191], v182 offset:50176
	ds_read_b128 v[192:195], v182 offset:51200
	ds_read_b128 v[200:203], v182 offset:52224
	ds_read_b128 v[204:207], v182 offset:53248
	ds_read_b128 v[208:211], v182 offset:54272
	ds_read_b128 v[212:215], v182 offset:55296
	ds_read_b128 v[216:219], v182 offset:56320
	global_load_lds_dwordx4 v152, s[34:35]
	s_add_i32 m0, s36, 0x2000
	s_add_i32 s36, s58, s38
	global_load_lds_dwordx4 v156, s[34:35]
	s_add_u32 s34, s34, 0x80000
	s_addc_u32 s35, s35, 0
	s_mov_b32 m0, s36
	s_nop 0
	global_load_lds_dwordx4 v152, s[34:35]
	s_add_i32 m0, s36, 0x2000
	s_nop 0
	global_load_lds_dwordx4 v156, s[34:35]
	s_waitcnt vmcnt(6)
	s_waitcnt lgkmcnt(0)
	s_setprio 1
	s_barrier
	v_mfma_f32_16x16x32_bf16 v[62:65], v[130:133], v[184:187], v[62:65]
	v_mfma_f32_16x16x32_bf16 v[58:61], v[138:141], v[184:187], v[58:61]
	v_mfma_f32_16x16x32_bf16 v[46:49], v[130:133], v[192:195], v[46:49]
	v_mfma_f32_16x16x32_bf16 v[42:45], v[138:141], v[192:195], v[42:45]
	v_mfma_f32_16x16x32_bf16 v[30:33], v[130:133], v[204:207], v[30:33]
	v_mfma_f32_16x16x32_bf16 v[26:29], v[138:141], v[204:207], v[26:29]
	v_mfma_f32_16x16x32_bf16 v[14:17], v[130:133], v[212:215], v[14:17]
	v_mfma_f32_16x16x32_bf16 v[10:13], v[138:141], v[212:215], v[10:13]
	v_mfma_f32_16x16x32_bf16 v[62:65], v[134:137], v[188:191], v[62:65]
	v_mfma_f32_16x16x32_bf16 v[58:61], v[142:145], v[188:191], v[58:61]
	v_mfma_f32_16x16x32_bf16 v[46:49], v[134:137], v[200:203], v[46:49]
	v_mfma_f32_16x16x32_bf16 v[42:45], v[142:145], v[200:203], v[42:45]
	v_mfma_f32_16x16x32_bf16 v[30:33], v[134:137], v[208:211], v[30:33]
	v_mfma_f32_16x16x32_bf16 v[26:29], v[142:145], v[208:211], v[26:29]
	v_mfma_f32_16x16x32_bf16 v[14:17], v[134:137], v[216:219], v[14:17]
	v_mfma_f32_16x16x32_bf16 v[10:13], v[142:145], v[216:219], v[10:13]
	v_mfma_f32_16x16x32_bf16 v[54:57], v[146:149], v[184:187], v[54:57]
	v_mfma_f32_16x16x32_bf16 v[50:53], v[170:173], v[184:187], v[50:53]
	v_mfma_f32_16x16x32_bf16 v[38:41], v[146:149], v[192:195], v[38:41]
	v_mfma_f32_16x16x32_bf16 v[34:37], v[170:173], v[192:195], v[34:37]
	v_mfma_f32_16x16x32_bf16 v[22:25], v[146:149], v[204:207], v[22:25]
	v_mfma_f32_16x16x32_bf16 v[18:21], v[170:173], v[204:207], v[18:21]
	v_mfma_f32_16x16x32_bf16 v[6:9], v[146:149], v[212:215], v[6:9]
	v_mfma_f32_16x16x32_bf16 v[2:5], v[170:173], v[212:215], v[2:5]
	v_mfma_f32_16x16x32_bf16 v[54:57], v[166:169], v[188:191], v[54:57]
	v_mfma_f32_16x16x32_bf16 v[50:53], v[174:177], v[188:191], v[50:53]
	v_mfma_f32_16x16x32_bf16 v[38:41], v[166:169], v[200:203], v[38:41]
	v_mfma_f32_16x16x32_bf16 v[34:37], v[174:177], v[200:203], v[34:37]
	v_mfma_f32_16x16x32_bf16 v[22:25], v[166:169], v[208:211], v[22:25]
	v_mfma_f32_16x16x32_bf16 v[18:21], v[174:177], v[208:211], v[18:21]
	v_mfma_f32_16x16x32_bf16 v[6:9], v[166:169], v[216:219], v[6:9]
	v_mfma_f32_16x16x32_bf16 v[2:5], v[174:177], v[216:219], v[2:5]
	s_barrier
	s_setprio 0
	s_add_i32 s56, s56, 2
	s_add_u32 s30, s30, 0x100
	s_addc_u32 s31, s31, 0
	s_add_u32 s52, s52, 0x100
	s_addc_u32 s53, s53, 0
	s_cmp_gt_u32 s56, 29
	.p2align 8

; #define PG8_STAGE(bufoff, gbase, voff) do { _Pragma("unroll") for (int _i = 0; _i < 2; ++_i) \
;         __builtin_amdgcn_global_load_lds((const unsigned*)((const char*)(gbase) + (voff)[_i]), (PG8_LAS unsigned*)(lds + (bufoff) + ldsw + _i * 8192), 16, 0, 0); } while (0)
; #define PG8_LDA(dst, b, h) do { _Pragma("unroll") for (int m = 0; m < 4; ++m) _Pragma("unroll") for (int k = 0; k < 2; ++k) dst[m][k] = *(const PG8_LAS bf16x8*)(lds + PG8_SA(b, h) + aoff + m * 2048 + k * 1024); } while (0)
; #define PG8_LDB(dst, b, h) do { _Pragma("unroll") for (int n = 0; n < 2; ++n) _Pragma("unroll") for (int k = 0; k < 2; ++k) dst[n][k] = *(const PG8_LAS bf16x8*)(lds + PG8_SB(b, h) + boff + n * 2048 + k * 1024); } while (0)
; #define PG8_WAIT_V(n) asm volatile("s_waitcnt vmcnt(" #n ")" ::: "memory")
; #define PG8_WAIT_L(n) asm volatile("s_waitcnt lgkmcnt(" #n ")" ::: "memory")
; #define PG8_BAR __builtin_amdgcn_s_barrier()
; #define PG8_SCHED __builtin_amdgcn_sched_barrier(0)
; template <class Epi, class Sched, bool ALIGN_EPI = false, bool SP2 = false>
; __device__ __forceinline__ void gemm_phase(PG8_LAS unsigned char* lds, const Gemm g, const Sched& S, const Epi& E) {
;     ...
;         const bool has_next = S.next(ui + 1, nxt);
;         const char* nA = has_next ? (const char*)g.A + (size_t)nxt.pm * tstep : cA; const char* nB = has_next ? (const char*)g.Bt + (size_t)nxt.pn * tstep : cB;
;         for (int t = 0; t < nt; t += 2) {
;             const bool last = (t == nt - 2);
;             const char* a1 = cA + (size_t)(t + 1) * kstep;
;             const char* a2 = last ? nA : cA + (size_t)(t + 2) * kstep; const char* b2 = last ? nB : cB + (size_t)(t + 2) * kstep;
;             const char* a3 = a2 + kstep; const char* b3 = b2 + kstep;
;             if (last && has_next) S.a_ready(nxt);
;             if constexpr (SP2) {
;             PG8_LDB(B0, 0, 0); PG8_LDB(B1, 0, 1); PG8_SCHED; PG8_LDA(At, 0, 0); PG8_STAGE(PG8_SA(1, 1), a1 + hstep, voffA);
;             PG8_WAIT_V(8); PG8_WAIT_L(0); PG8_BAR; PG8_MMA(0, 0, At, B0); PG8_MMA(0, 1, At, B1); PG8_BAR; PG8_SCHED;
;             PG8_LDA(At, 0, 1); PG8_STAGE(PG8_SB(0, 0), b2, voffB); PG8_STAGE(PG8_SB(0, 1), b2 + hstep, voffB); PG8_STAGE(PG8_SA(0, 0), a2, voffA);
;             PG8_WAIT_V(8); PG8_WAIT_L(0); PG8_BAR; PG8_MMA(1, 0, At, B0); PG8_MMA(1, 1, At, B1); PG8_BAR; PG8_SCHED;
.LBB0_883:
	s_ashr_i32 s15, s14, 31
	s_lshl_b64 s[24:25], s[14:15], 20
	s_add_u32 s24, s54, s24
	s_addc_u32 s25, s55, s25
	s_and_b64 s[26:27], s[0:1], exec
	s_cselect_b32 s15, s25, s31
	s_cselect_b32 s50, s24, s30
	s_ashr_i32 s13, s12, 31
	s_lshl_b64 s[26:27], s[12:13], 20
	s_add_u32 s26, s18, s26
	s_addc_u32 s27, s19, s27
	s_and_b64 s[36:37], s[0:1], exec
	s_cselect_b32 s13, s27, s35
	s_cselect_b32 s51, s26, s34
	s_add_u32 s30, s30, 0x80080
	s_addc_u32 s31, s31, 0
	s_add_u32 s52, s34, 0x100
	s_addc_u32 s53, s35, 0
	s_mov_b32 s56, -2
	s_waitcnt vmcnt(0)
	s_add_u32 s34, s30, 0xfff80000
	s_addc_u32 s35, s31, -1
	s_mov_b32 m0, s43
	s_nop 0
	global_load_lds_dwordx4 v178, s[34:35]
	s_mov_b32 m0, s44
	s_nop 0
	global_load_lds_dwordx4 v182, s[34:35]
	s_add_u32 s34, s34, 0x80
	s_addc_u32 s35, s35, 0
	ds_read_b128 v[130:133], v211
	ds_read_b128 v[134:137], v211 offset:1024
	ds_read_b128 v[138:141], v211 offset:2048
	ds_read_b128 v[142:145], v211 offset:3072
	ds_read_b128 v[146:149], v212
	ds_read_b128 v[150:153], v212 offset:1024
	ds_read_b128 v[154:157], v212 offset:2048
	ds_read_b128 v[158:161], v212 offset:3072
	s_cmp_eq_u32 s56, 28
	s_cselect_b32 s37, s15, s35
	s_cselect_b32 s36, s50, s34
	s_cselect_b32 s35, s13, s53
	s_cselect_b32 s34, s51, s52
	s_add_i32 m0, s29, 0xc000
	ds_read_b128 v[162:165], v213
	ds_read_b128 v[166:169], v213 offset:1024
	ds_read_b128 v[170:173], v213 offset:2048
	ds_read_b128 v[174:177], v213 offset:3072
	ds_read_b128 v[194:197], v213 offset:4096
	ds_read_b128 v[200:203], v213 offset:5120
	ds_read_b128 v[204:207], v213 offset:6144
	ds_read_b128 v[214:217], v213 offset:7168
	global_load_lds_dwordx4 v186, s[30:31]
	s_add_i32 m0, s29, 0xe000
	s_nop 0
	global_load_lds_dwordx4 v188, s[30:31]
	s_waitcnt vmcnt(8)
	s_waitcnt lgkmcnt(0)
	s_setprio 1
	s_barrier
	v_mfma_f32_16x16x32_bf16 v[126:129], v[130:133], v[162:165], 0
	v_mfma_f32_16x16x32_bf16 v[122:125], v[138:141], v[162:165], 0
	v_mfma_f32_16x16x32_bf16 v[110:113], v[130:133], v[170:173], 0
	v_mfma_f32_16x16x32_bf16 v[106:109], v[138:141], v[170:173], 0
	v_mfma_f32_16x16x32_bf16 v[94:97], v[130:133], v[194:197], 0
	v_mfma_f32_16x16x32_bf16 v[90:93], v[138:141], v[194:197], 0
	v_mfma_f32_16x16x32_bf16 v[78:81], v[130:133], v[204:207], 0
	v_mfma_f32_16x16x32_bf16 v[74:77], v[138:141], v[204:207], 0
	v_mfma_f32_16x16x32_bf16 v[126:129], v[134:137], v[166:169], v[126:129]
	v_mfma_f32_16x16x32_bf16 v[122:125], v[142:145], v[166:169], v[122:125]
	v_mfma_f32_16x16x32_bf16 v[110:113], v[134:137], v[174:177], v[110:113]
	v_mfma_f32_16x16x32_bf16 v[106:109], v[142:145], v[174:177], v[106:109]
	v_mfma_f32_16x16x32_bf16 v[94:97], v[134:137], v[200:203], v[94:97]
	v_mfma_f32_16x16x32_bf16 v[90:93], v[142:145], v[200:203], v[90:93]
	v_mfma_f32_16x16x32_bf16 v[78:81], v[134:137], v[214:217], v[78:81]
	v_mfma_f32_16x16x32_bf16 v[74:77], v[142:145], v[214:217], v[74:77]
	v_mfma_f32_16x16x32_bf16 v[118:121], v[146:149], v[162:165], 0
	v_mfma_f32_16x16x32_bf16 v[114:117], v[154:157], v[162:165], 0
	v_mfma_f32_16x16x32_bf16 v[102:105], v[146:149], v[170:173], 0
	v_mfma_f32_16x16x32_bf16 v[98:101], v[154:157], v[170:173], 0
	v_mfma_f32_16x16x32_bf16 v[86:89], v[146:149], v[194:197], 0
	v_mfma_f32_16x16x32_bf16 v[82:85], v[154:157], v[194:197], 0
	v_mfma_f32_16x16x32_bf16 v[70:73], v[146:149], v[204:207], 0
	v_mfma_f32_16x16x32_bf16 v[66:69], v[154:157], v[204:207], 0
	v_mfma_f32_16x16x32_bf16 v[118:121], v[150:153], v[166:169], v[118:121]
	v_mfma_f32_16x16x32_bf16 v[114:117], v[158:161], v[166:169], v[114:117]
	v_mfma_f32_16x16x32_bf16 v[102:105], v[150:153], v[174:177], v[102:105]
	v_mfma_f32_16x16x32_bf16 v[98:101], v[158:161], v[174:177], v[98:101]
	v_mfma_f32_16x16x32_bf16 v[86:89], v[150:153], v[200:203], v[86:89]
	v_mfma_f32_16x16x32_bf16 v[82:85], v[158:161], v[200:203], v[82:85]
	v_mfma_f32_16x16x32_bf16 v[70:73], v[150:153], v[214:217], v[70:73]
	v_mfma_f32_16x16x32_bf16 v[66:69], v[158:161], v[214:217], v[66:69]
	s_barrier
	s_setprio 0
	s_add_i32 s57, s46, s38
	s_mov_b32 m0, s57
	ds_read_b128 v[162:165], v213 offset:16384
	ds_read_b128 v[166:169], v213 offset:17408
	ds_read_b128 v[170:173], v213 offset:18432
	ds_read_b128 v[174:177], v213 offset:19456
	ds_read_b128 v[194:197], v213 offset:20480
	ds_read_b128 v[200:203], v213 offset:21504
	ds_read_b128 v[204:207], v213 offset:22528
	ds_read_b128 v[214:217], v213 offset:23552
	global_load_lds_dwordx4 v180, s[34:35]
	s_add_i32 m0, s57, 0x2000
	s_add_u32 s58, s34, 0x80000
	s_addc_u32 s59, s35, 0
	s_add_i32 s57, s47, s38
	global_load_lds_dwordx4 v184, s[34:35]
	s_mov_b32 m0, s57
	s_nop 0
	global_load_lds_dwordx4 v180, s[58:59]
	s_add_i32 m0, s57, 0x2000
	s_nop 0
	global_load_lds_dwordx4 v184, s[58:59]
	s_waitcnt vmcnt(6)
	s_waitcnt lgkmcnt(0)
	s_setprio 1
	s_barrier
; #define PG8_STAGE(bufoff, gbase, voff) do { _Pragma("unroll") for (int _i = 0; _i < 2; ++_i) \
;         __builtin_amdgcn_global_load_lds((const unsigned*)((const char*)(gbase) + (voff)[_i]), (PG8_LAS unsigned*)(lds + (bufoff) + ldsw + _i * 8192), 16, 0, 0); } while (0)
; #define PG8_LDA(dst, b, h) do { _Pragma("unroll") for (int m = 0; m < 4; ++m) _Pragma("unroll") for (int k = 0; k < 2; ++k) dst[m][k] = *(const PG8_LAS bf16x8*)(lds + PG8_SA(b, h) + aoff + m * 2048 + k * 1024); } while (0)
; #define PG8_LDB(dst, b, h) do { _Pragma("unroll") for (int n = 0; n < 2; ++n) _Pragma("unroll") for (int k = 0; k < 2; ++k) dst[n][k] = *(const PG8_LAS bf16x8*)(lds + PG8_SB(b, h) + boff + n * 2048 + k * 1024); } while (0)
; #define PG8_MMA(ai, bj, At, Bt) do { __builtin_amdgcn_s_setprio(1); _Pragma("unroll") for (int m = 0; m < 4; ++m) _Pragma("unroll") for (int n = 0; n < 2; ++n) _Pragma("unroll") for (int k = 0; k < 2; ++k) \
;         acc[ai][bj][m][n] = __builtin_amdgcn_mfma_f32_16x16x32_bf16(Bt[n][k], At[m][k], acc[ai][bj][m][n], 0, 0, 0); __builtin_amdgcn_s_setprio(0); } while (0)
; #define PG8_WAIT_V(n) asm volatile("s_waitcnt vmcnt(" #n ")" ::: "memory")
; #define PG8_WAIT_L(n) asm volatile("s_waitcnt lgkmcnt(" #n ")" ::: "memory")
; #define PG8_BAR __builtin_amdgcn_s_barrier()
; #define PG8_SCHED __builtin_amdgcn_sched_barrier(0)
; template <class Epi, class Sched, bool ALIGN_EPI = false, bool SP2 = false>
; __device__ __forceinline__ void gemm_phase(PG8_LAS unsigned char* lds, const Gemm g, const Sched& S, const Epi& E) {
;     ...
;             PG8_WAIT_V(8); PG8_WAIT_L(0); PG8_BAR; PG8_MMA(0, 0, At, B0); PG8_MMA(0, 1, At, B1); PG8_BAR; PG8_SCHED;
;             PG8_LDA(At, 0, 1); PG8_STAGE(PG8_SB(0, 0), b2, voffB); PG8_STAGE(PG8_SB(0, 1), b2 + hstep, voffB); PG8_STAGE(PG8_SA(0, 0), a2, voffA);
;             PG8_WAIT_V(8); PG8_WAIT_L(0); PG8_BAR; PG8_MMA(1, 0, At, B0); PG8_MMA(1, 1, At, B1); PG8_BAR; PG8_SCHED;
;             PG8_LDB(B0, 1, 0); PG8_LDB(B1, 1, 1); PG8_SCHED; PG8_LDA(At, 1, 0); PG8_STAGE(PG8_SA(0, 1), a2 + hstep, voffA);
;             PG8_WAIT_V(8); PG8_WAIT_L(0); PG8_BAR; PG8_MMA(0, 0, At, B0); PG8_MMA(0, 1, At, B1); PG8_BAR; PG8_SCHED;
	v_mfma_f32_16x16x32_bf16 v[62:65], v[130:133], v[162:165], 0
	v_mfma_f32_16x16x32_bf16 v[58:61], v[138:141], v[162:165], 0
	v_mfma_f32_16x16x32_bf16 v[46:49], v[130:133], v[170:173], 0
	v_mfma_f32_16x16x32_bf16 v[42:45], v[138:141], v[170:173], 0
	v_mfma_f32_16x16x32_bf16 v[30:33], v[130:133], v[194:197], 0
	v_mfma_f32_16x16x32_bf16 v[26:29], v[138:141], v[194:197], 0
	v_mfma_f32_16x16x32_bf16 v[14:17], v[130:133], v[204:207], 0
	v_mfma_f32_16x16x32_bf16 v[10:13], v[138:141], v[204:207], 0
	v_mfma_f32_16x16x32_bf16 v[62:65], v[134:137], v[166:169], v[62:65]
	v_mfma_f32_16x16x32_bf16 v[58:61], v[142:145], v[166:169], v[58:61]
	v_mfma_f32_16x16x32_bf16 v[46:49], v[134:137], v[174:177], v[46:49]
	v_mfma_f32_16x16x32_bf16 v[42:45], v[142:145], v[174:177], v[42:45]
	v_mfma_f32_16x16x32_bf16 v[30:33], v[134:137], v[200:203], v[30:33]
	v_mfma_f32_16x16x32_bf16 v[26:29], v[142:145], v[200:203], v[26:29]
	v_mfma_f32_16x16x32_bf16 v[14:17], v[134:137], v[214:217], v[14:17]
	v_mfma_f32_16x16x32_bf16 v[10:13], v[142:145], v[214:217], v[10:13]
	v_mfma_f32_16x16x32_bf16 v[54:57], v[146:149], v[162:165], 0
	v_mfma_f32_16x16x32_bf16 v[50:53], v[154:157], v[162:165], 0
	v_mfma_f32_16x16x32_bf16 v[38:41], v[146:149], v[170:173], 0
	v_mfma_f32_16x16x32_bf16 v[34:37], v[154:157], v[170:173], 0
	v_mfma_f32_16x16x32_bf16 v[22:25], v[146:149], v[194:197], 0
	v_mfma_f32_16x16x32_bf16 v[18:21], v[154:157], v[194:197], 0
	v_mfma_f32_16x16x32_bf16 v[6:9], v[146:149], v[204:207], 0
	v_mfma_f32_16x16x32_bf16 v[2:5], v[154:157], v[204:207], 0
	v_mfma_f32_16x16x32_bf16 v[54:57], v[150:153], v[166:169], v[54:57]
	v_mfma_f32_16x16x32_bf16 v[50:53], v[158:161], v[166:169], v[50:53]
	v_mfma_f32_16x16x32_bf16 v[38:41], v[150:153], v[174:177], v[38:41]
	v_mfma_f32_16x16x32_bf16 v[34:37], v[158:161], v[174:177], v[34:37]
	v_mfma_f32_16x16x32_bf16 v[22:25], v[150:153], v[200:203], v[22:25]
	v_mfma_f32_16x16x32_bf16 v[18:21], v[158:161], v[200:203], v[18:21]
	v_mfma_f32_16x16x32_bf16 v[6:9], v[150:153], v[214:217], v[6:9]
	v_mfma_f32_16x16x32_bf16 v[2:5], v[158:161], v[214:217], v[2:5]
	s_barrier
	s_setprio 0
	s_mov_b32 m0, s29
	s_nop 0
	global_load_lds_dwordx4 v178, s[36:37]
	s_mov_b32 m0, s39
	s_nop 0
	global_load_lds_dwordx4 v182, s[36:37]
	s_add_i32 s57, 0, 0x18000
	s_add_i32 s58, 0, 0x1c000
	v_add_u32_e32 v142, s57, v199
	v_add_u32_e32 v158, s58, v199
	ds_read_b128 v[130:133], v142
	ds_read_b128 v[134:137], v142 offset:1024
	ds_read_b128 v[138:141], v142 offset:2048
	ds_read_b128 v[142:145], v142 offset:3072
	ds_read_b128 v[146:149], v158
	ds_read_b128 v[150:153], v158 offset:1024
	ds_read_b128 v[154:157], v158 offset:2048
	ds_read_b128 v[158:161], v158 offset:3072
	s_add_u32 s36, s36, 0x80000
	s_addc_u32 s37, s37, 0
	s_mov_b32 m0, s40
	ds_read_b128 v[162:165], v213 offset:32768
	ds_read_b128 v[166:169], v213 offset:33792
	ds_read_b128 v[170:173], v213 offset:34816
	ds_read_b128 v[174:177], v213 offset:35840
	ds_read_b128 v[194:197], v213 offset:36864
	ds_read_b128 v[200:203], v213 offset:37888
	ds_read_b128 v[204:207], v213 offset:38912
	ds_read_b128 v[214:217], v213 offset:39936
	global_load_lds_dwordx4 v178, s[36:37]
	s_mov_b32 m0, s41
	s_nop 0
	global_load_lds_dwordx4 v182, s[36:37]
	s_waitcnt vmcnt(8)
	s_waitcnt lgkmcnt(0)
	s_setprio 1
	s_barrier
; #define PG8_STAGE(bufoff, gbase, voff) do { _Pragma("unroll") for (int _i = 0; _i < 2; ++_i) \
;         __builtin_amdgcn_global_load_lds((const unsigned*)((const char*)(gbase) + (voff)[_i]), (PG8_LAS unsigned*)(lds + (bufoff) + ldsw + _i * 8192), 16, 0, 0); } while (0)
; #define PG8_LDA(dst, b, h) do { _Pragma("unroll") for (int m = 0; m < 4; ++m) _Pragma("unroll") for (int k = 0; k < 2; ++k) dst[m][k] = *(const PG8_LAS bf16x8*)(lds + PG8_SA(b, h) + aoff + m * 2048 + k * 1024); } while (0)
; #define PG8_MMA(ai, bj, At, Bt) do { __builtin_amdgcn_s_setprio(1); _Pragma("unroll") for (int m = 0; m < 4; ++m) _Pragma("unroll") for (int n = 0; n < 2; ++n) _Pragma("unroll") for (int k = 0; k < 2; ++k) \
;         acc[ai][bj][m][n] = __builtin_amdgcn_mfma_f32_16x16x32_bf16(Bt[n][k], At[m][k], acc[ai][bj][m][n], 0, 0, 0); __builtin_amdgcn_s_setprio(0); } while (0)
; #define PG8_WAIT_V(n) asm volatile("s_waitcnt vmcnt(" #n ")" ::: "memory")
; #define PG8_WAIT_L(n) asm volatile("s_waitcnt lgkmcnt(" #n ")" ::: "memory")
; #define PG8_BAR __builtin_amdgcn_s_barrier()
; #define PG8_SCHED __builtin_amdgcn_sched_barrier(0)
; template <class Epi, class Sched, bool ALIGN_EPI = false, bool SP2 = false>
; __device__ __forceinline__ void gemm_phase(PG8_LAS unsigned char* lds, const Gemm g, const Sched& S, const Epi& E) {
;     ...
;             PG8_WAIT_V(8); PG8_WAIT_L(0); PG8_BAR; PG8_MMA(0, 0, At, B0); PG8_MMA(0, 1, At, B1); PG8_BAR; PG8_SCHED;
;             PG8_LDA(At, 1, 1); PG8_STAGE(PG8_SB(1, 0), b3, voffB); PG8_STAGE(PG8_SB(1, 1), b3 + hstep, voffB); PG8_STAGE(PG8_SA(1, 0), a3, voffA);
;             PG8_WAIT_V(8); PG8_WAIT_L(0); PG8_BAR; PG8_MMA(1, 0, At, B0); PG8_MMA(1, 1, At, B1); PG8_BAR; PG8_SCHED;
	v_mfma_f32_16x16x32_bf16 v[126:129], v[130:133], v[162:165], v[126:129]
	v_mfma_f32_16x16x32_bf16 v[122:125], v[138:141], v[162:165], v[122:125]
	v_mfma_f32_16x16x32_bf16 v[110:113], v[130:133], v[170:173], v[110:113]
	v_mfma_f32_16x16x32_bf16 v[106:109], v[138:141], v[170:173], v[106:109]
	v_mfma_f32_16x16x32_bf16 v[94:97], v[130:133], v[194:197], v[94:97]
	v_mfma_f32_16x16x32_bf16 v[90:93], v[138:141], v[194:197], v[90:93]
	v_mfma_f32_16x16x32_bf16 v[78:81], v[130:133], v[204:207], v[78:81]
	v_mfma_f32_16x16x32_bf16 v[74:77], v[138:141], v[204:207], v[74:77]
	v_mfma_f32_16x16x32_bf16 v[126:129], v[134:137], v[166:169], v[126:129]
	v_mfma_f32_16x16x32_bf16 v[122:125], v[142:145], v[166:169], v[122:125]
	v_mfma_f32_16x16x32_bf16 v[110:113], v[134:137], v[174:177], v[110:113]
	v_mfma_f32_16x16x32_bf16 v[106:109], v[142:145], v[174:177], v[106:109]
	v_mfma_f32_16x16x32_bf16 v[94:97], v[134:137], v[200:203], v[94:97]
	v_mfma_f32_16x16x32_bf16 v[90:93], v[142:145], v[200:203], v[90:93]
	v_mfma_f32_16x16x32_bf16 v[78:81], v[134:137], v[214:217], v[78:81]
	v_mfma_f32_16x16x32_bf16 v[74:77], v[142:145], v[214:217], v[74:77]
	v_mfma_f32_16x16x32_bf16 v[118:121], v[146:149], v[162:165], v[118:121]
	v_mfma_f32_16x16x32_bf16 v[114:117], v[154:157], v[162:165], v[114:117]
	v_mfma_f32_16x16x32_bf16 v[102:105], v[146:149], v[170:173], v[102:105]
	v_mfma_f32_16x16x32_bf16 v[98:101], v[154:157], v[170:173], v[98:101]
	v_mfma_f32_16x16x32_bf16 v[86:89], v[146:149], v[194:197], v[86:89]
	v_mfma_f32_16x16x32_bf16 v[82:85], v[154:157], v[194:197], v[82:85]
	v_mfma_f32_16x16x32_bf16 v[70:73], v[146:149], v[204:207], v[70:73]
	v_mfma_f32_16x16x32_bf16 v[66:69], v[154:157], v[204:207], v[66:69]
	v_mfma_f32_16x16x32_bf16 v[118:121], v[150:153], v[166:169], v[118:121]
	v_mfma_f32_16x16x32_bf16 v[114:117], v[158:161], v[166:169], v[114:117]
	v_mfma_f32_16x16x32_bf16 v[102:105], v[150:153], v[174:177], v[102:105]
	v_mfma_f32_16x16x32_bf16 v[98:101], v[158:161], v[174:177], v[98:101]
	v_mfma_f32_16x16x32_bf16 v[86:89], v[150:153], v[200:203], v[86:89]
	v_mfma_f32_16x16x32_bf16 v[82:85], v[158:161], v[200:203], v[82:85]
	v_mfma_f32_16x16x32_bf16 v[70:73], v[150:153], v[214:217], v[70:73]
	v_mfma_f32_16x16x32_bf16 v[66:69], v[158:161], v[214:217], v[66:69]
	s_barrier
	s_setprio 0
	s_add_i32 s36, s57, s38
	s_add_u32 s34, s34, 0x80
	s_addc_u32 s35, s35, 0
	s_mov_b32 m0, s36
	ds_read_b128 v[162:165], v213 offset:49152
	ds_read_b128 v[166:169], v213 offset:50176
	ds_read_b128 v[170:173], v213 offset:51200
	ds_read_b128 v[174:177], v213 offset:52224
	ds_read_b128 v[194:197], v213 offset:53248
	ds_read_b128 v[200:203], v213 offset:54272
	ds_read_b128 v[204:207], v213 offset:55296
	ds_read_b128 v[214:217], v213 offset:56320
	global_load_lds_dwordx4 v180, s[34:35]
	s_add_i32 m0, s36, 0x2000
	s_add_i32 s36, s58, s38
	global_load_lds_dwordx4 v184, s[34:35]
	s_add_u32 s34, s34, 0x80000
	s_addc_u32 s35, s35, 0
	s_mov_b32 m0, s36
	s_nop 0
	global_load_lds_dwordx4 v180, s[34:35]
	s_add_i32 m0, s36, 0x2000
	s_nop 0
	global_load_lds_dwordx4 v184, s[34:35]
	s_waitcnt vmcnt(6)
	s_waitcnt lgkmcnt(0)
	s_setprio 1
	s_barrier
	v_mfma_f32_16x16x32_bf16 v[62:65], v[130:133], v[162:165], v[62:65]
	v_mfma_f32_16x16x32_bf16 v[58:61], v[138:141], v[162:165], v[58:61]
	v_mfma_f32_16x16x32_bf16 v[46:49], v[130:133], v[170:173], v[46:49]
	v_mfma_f32_16x16x32_bf16 v[42:45], v[138:141], v[170:173], v[42:45]
	v_mfma_f32_16x16x32_bf16 v[30:33], v[130:133], v[194:197], v[30:33]
	v_mfma_f32_16x16x32_bf16 v[26:29], v[138:141], v[194:197], v[26:29]
	v_mfma_f32_16x16x32_bf16 v[14:17], v[130:133], v[204:207], v[14:17]
	v_mfma_f32_16x16x32_bf16 v[10:13], v[138:141], v[204:207], v[10:13]
	v_mfma_f32_16x16x32_bf16 v[62:65], v[134:137], v[166:169], v[62:65]
	v_mfma_f32_16x16x32_bf16 v[58:61], v[142:145], v[166:169], v[58:61]
	v_mfma_f32_16x16x32_bf16 v[46:49], v[134:137], v[174:177], v[46:49]
	v_mfma_f32_16x16x32_bf16 v[42:45], v[142:145], v[174:177], v[42:45]
	v_mfma_f32_16x16x32_bf16 v[30:33], v[134:137], v[200:203], v[30:33]
	v_mfma_f32_16x16x32_bf16 v[26:29], v[142:145], v[200:203], v[26:29]
	v_mfma_f32_16x16x32_bf16 v[14:17], v[134:137], v[214:217], v[14:17]
	v_mfma_f32_16x16x32_bf16 v[10:13], v[142:145], v[214:217], v[10:13]
	v_mfma_f32_16x16x32_bf16 v[54:57], v[146:149], v[162:165], v[54:57]
	v_mfma_f32_16x16x32_bf16 v[50:53], v[154:157], v[162:165], v[50:53]
	v_mfma_f32_16x16x32_bf16 v[38:41], v[146:149], v[170:173], v[38:41]
	v_mfma_f32_16x16x32_bf16 v[34:37], v[154:157], v[170:173], v[34:37]
	v_mfma_f32_16x16x32_bf16 v[22:25], v[146:149], v[194:197], v[22:25]
	v_mfma_f32_16x16x32_bf16 v[18:21], v[154:157], v[194:197], v[18:21]
	v_mfma_f32_16x16x32_bf16 v[6:9], v[146:149], v[204:207], v[6:9]
	v_mfma_f32_16x16x32_bf16 v[2:5], v[154:157], v[204:207], v[2:5]
	v_mfma_f32_16x16x32_bf16 v[54:57], v[150:153], v[166:169], v[54:57]
	v_mfma_f32_16x16x32_bf16 v[50:53], v[158:161], v[166:169], v[50:53]
	v_mfma_f32_16x16x32_bf16 v[38:41], v[150:153], v[174:177], v[38:41]
	v_mfma_f32_16x16x32_bf16 v[34:37], v[158:161], v[174:177], v[34:37]
	v_mfma_f32_16x16x32_bf16 v[22:25], v[150:153], v[200:203], v[22:25]
	v_mfma_f32_16x16x32_bf16 v[18:21], v[158:161], v[200:203], v[18:21]
	v_mfma_f32_16x16x32_bf16 v[6:9], v[150:153], v[214:217], v[6:9]
	v_mfma_f32_16x16x32_bf16 v[2:5], v[158:161], v[214:217], v[2:5]
	s_barrier
	s_setprio 0
	s_add_i32 s56, s56, 2
	s_add_u32 s30, s30, 0x100
	s_addc_u32 s31, s31, 0
	s_add_u32 s52, s52, 0x100
	s_addc_u32 s53, s53, 0
	s_cmp_gt_u32 s56, 29
	.p2align 8

; #define PG8_STAGE(bufoff, gbase, voff) do { _Pragma("unroll") for (int _i = 0; _i < 2; ++_i) \
;         __builtin_amdgcn_global_load_lds((const unsigned*)((const char*)(gbase) + (voff)[_i]), (PG8_LAS unsigned*)(lds + (bufoff) + ldsw + _i * 8192), 16, 0, 0); } while (0)
; #define PG8_LDA(dst, b, h) do { _Pragma("unroll") for (int m = 0; m < 4; ++m) _Pragma("unroll") for (int k = 0; k < 2; ++k) dst[m][k] = *(const PG8_LAS bf16x8*)(lds + PG8_SA(b, h) + aoff + m * 2048 + k * 1024); } while (0)
; #define PG8_LDB(dst, b, h) do { _Pragma("unroll") for (int n = 0; n < 2; ++n) _Pragma("unroll") for (int k = 0; k < 2; ++k) dst[n][k] = *(const PG8_LAS bf16x8*)(lds + PG8_SB(b, h) + boff + n * 2048 + k * 1024); } while (0)
; #define PG8_WAIT_V(n) asm volatile("s_waitcnt vmcnt(" #n ")" ::: "memory")
; #define PG8_WAIT_L(n) asm volatile("s_waitcnt lgkmcnt(" #n ")" ::: "memory")
; #define PG8_BAR __builtin_amdgcn_s_barrier()
; #define PG8_SCHED __builtin_amdgcn_sched_barrier(0)
; template <class Epi, class Sched, bool ALIGN_EPI = false, bool SP2 = false>
; __device__ __forceinline__ void gemm_phase(PG8_LAS unsigned char* lds, const Gemm g, const Sched& S, const Epi& E) {
;     ...
;         const bool has_next = S.next(ui + 1, nxt);
;         const char* nA = has_next ? (const char*)g.A + (size_t)nxt.pm * tstep : cA; const char* nB = has_next ? (const char*)g.Bt + (size_t)nxt.pn * tstep : cB;
;         for (int t = 0; t < nt; t += 2) {
;             const bool last = (t == nt - 2);
;             const char* a1 = cA + (size_t)(t + 1) * kstep;
;             const char* a2 = last ? nA : cA + (size_t)(t + 2) * kstep; const char* b2 = last ? nB : cB + (size_t)(t + 2) * kstep;
;             const char* a3 = a2 + kstep; const char* b3 = b2 + kstep;
;             if (last && has_next) S.a_ready(nxt);
;             if constexpr (SP2) {
;             PG8_LDB(B0, 0, 0); PG8_LDB(B1, 0, 1); PG8_SCHED; PG8_LDA(At, 0, 0); PG8_STAGE(PG8_SA(1, 1), a1 + hstep, voffA);
;             PG8_WAIT_V(8); PG8_WAIT_L(0); PG8_BAR; PG8_MMA(0, 0, At, B0); PG8_MMA(0, 1, At, B1); PG8_BAR; PG8_SCHED;
;             PG8_LDA(At, 0, 1); PG8_STAGE(PG8_SB(0, 0), b2, voffB); PG8_STAGE(PG8_SB(0, 1), b2 + hstep, voffB); PG8_STAGE(PG8_SA(0, 0), a2, voffA);
;             PG8_WAIT_V(8); PG8_WAIT_L(0); PG8_BAR; PG8_MMA(1, 0, At, B0); PG8_MMA(1, 1, At, B1); PG8_BAR; PG8_SCHED;
.LBB0_958:
	s_ashr_i32 s13, s12, 31
	s_lshl_b64 s[14:15], s[12:13], 21
	s_add_u32 s14, s78, s14
	s_addc_u32 s15, s79, s15
	s_and_b64 s[24:25], s[0:1], exec
	s_cselect_b32 s13, s15, s29
	s_cselect_b32 s47, s14, s28
	s_ashr_i32 s11, s10, 31
	s_lshl_b64 s[24:25], s[10:11], 21
	s_add_u32 s24, s16, s24
	s_addc_u32 s25, s17, s25
	s_and_b64 s[34:35], s[0:1], exec
	s_cselect_b32 s11, s25, s31
	s_cselect_b32 s48, s24, s30
	s_add_u32 s28, s28, 0x100080
	s_addc_u32 s29, s29, 0
	s_add_u32 s49, s30, 0x100
	s_addc_u32 s50, s31, 0
	s_mov_b32 s51, -2
	s_add_u32 s30, s28, 0xfff00000
	s_addc_u32 s31, s29, -1
	s_mov_b32 m0, s41
	s_nop 0
	global_load_lds_dwordx4 v138, s[30:31]
	s_mov_b32 m0, s42
	s_nop 0
	global_load_lds_dwordx4 v142, s[30:31]
	s_add_u32 s30, s30, 0x80
	s_addc_u32 s31, s31, 0
	ds_read_b128 v[130:133], v164
	ds_read_b128 v[134:137], v164 offset:1024
	ds_read_b128 v[154:157], v164 offset:2048
	ds_read_b128 v[158:161], v164 offset:3072
	ds_read_b128 v[168:171], v165
	ds_read_b128 v[172:175], v165 offset:1024
	ds_read_b128 v[176:179], v165 offset:2048
	ds_read_b128 v[180:183], v165 offset:3072
	s_cmp_eq_u32 s51, 60
	s_cselect_b32 s35, s13, s31
	s_cselect_b32 s34, s47, s30
	s_cselect_b32 s31, s11, s50
	s_cselect_b32 s30, s48, s49
	s_add_i32 m0, s27, 0xc000
	ds_read_b128 v[184:187], v166
	ds_read_b128 v[188:191], v166 offset:1024
	ds_read_b128 v[192:195], v166 offset:2048
	ds_read_b128 v[200:203], v166 offset:3072
	ds_read_b128 v[204:207], v166 offset:4096
	ds_read_b128 v[208:211], v166 offset:5120
	ds_read_b128 v[212:215], v166 offset:6144
	ds_read_b128 v[216:219], v166 offset:7168
	global_load_lds_dwordx4 v146, s[28:29]
	s_add_i32 m0, s27, 0xe000
	s_nop 0
	global_load_lds_dwordx4 v148, s[28:29]
	s_waitcnt vmcnt(8)
	s_waitcnt lgkmcnt(0)
	s_setprio 1
	s_barrier
	v_mfma_f32_16x16x32_bf16 v[126:129], v[130:133], v[184:187], 0
	v_mfma_f32_16x16x32_bf16 v[122:125], v[154:157], v[184:187], 0
	v_mfma_f32_16x16x32_bf16 v[118:121], v[130:133], v[192:195], 0
	v_mfma_f32_16x16x32_bf16 v[114:117], v[154:157], v[192:195], 0
	v_mfma_f32_16x16x32_bf16 v[110:113], v[130:133], v[204:207], 0
	v_mfma_f32_16x16x32_bf16 v[102:105], v[154:157], v[204:207], 0
	v_mfma_f32_16x16x32_bf16 v[82:85], v[130:133], v[212:215], 0
	v_mfma_f32_16x16x32_bf16 v[74:77], v[154:157], v[212:215], 0
	v_mfma_f32_16x16x32_bf16 v[126:129], v[134:137], v[188:191], v[126:129]
	v_mfma_f32_16x16x32_bf16 v[122:125], v[158:161], v[188:191], v[122:125]
	v_mfma_f32_16x16x32_bf16 v[118:121], v[134:137], v[200:203], v[118:121]
	v_mfma_f32_16x16x32_bf16 v[114:117], v[158:161], v[200:203], v[114:117]
	v_mfma_f32_16x16x32_bf16 v[110:113], v[134:137], v[208:211], v[110:113]
	v_mfma_f32_16x16x32_bf16 v[102:105], v[158:161], v[208:211], v[102:105]
	v_mfma_f32_16x16x32_bf16 v[82:85], v[134:137], v[216:219], v[82:85]
	v_mfma_f32_16x16x32_bf16 v[74:77], v[158:161], v[216:219], v[74:77]
	v_mfma_f32_16x16x32_bf16 v[106:109], v[168:171], v[184:187], 0
	v_mfma_f32_16x16x32_bf16 v[98:101], v[176:179], v[184:187], 0
	v_mfma_f32_16x16x32_bf16 v[94:97], v[168:171], v[192:195], 0
	v_mfma_f32_16x16x32_bf16 v[90:93], v[176:179], v[192:195], 0
	v_mfma_f32_16x16x32_bf16 v[86:89], v[168:171], v[204:207], 0
	v_mfma_f32_16x16x32_bf16 v[78:81], v[176:179], v[204:207], 0
	v_mfma_f32_16x16x32_bf16 v[70:73], v[168:171], v[212:215], 0
	v_mfma_f32_16x16x32_bf16 v[66:69], v[176:179], v[212:215], 0
	v_mfma_f32_16x16x32_bf16 v[106:109], v[172:175], v[188:191], v[106:109]
	v_mfma_f32_16x16x32_bf16 v[98:101], v[180:183], v[188:191], v[98:101]
	v_mfma_f32_16x16x32_bf16 v[94:97], v[172:175], v[200:203], v[94:97]
	v_mfma_f32_16x16x32_bf16 v[90:93], v[180:183], v[200:203], v[90:93]
	v_mfma_f32_16x16x32_bf16 v[86:89], v[172:175], v[208:211], v[86:89]
	v_mfma_f32_16x16x32_bf16 v[78:81], v[180:183], v[208:211], v[78:81]
	v_mfma_f32_16x16x32_bf16 v[70:73], v[172:175], v[216:219], v[70:73]
	v_mfma_f32_16x16x32_bf16 v[66:69], v[180:183], v[216:219], v[66:69]
	s_barrier
	s_setprio 0
	s_add_i32 s52, s44, s36
	s_mov_b32 m0, s52
	ds_read_b128 v[184:187], v166 offset:16384
	ds_read_b128 v[188:191], v166 offset:17408
	ds_read_b128 v[192:195], v166 offset:18432
	ds_read_b128 v[200:203], v166 offset:19456
	ds_read_b128 v[204:207], v166 offset:20480
	ds_read_b128 v[208:211], v166 offset:21504
	ds_read_b128 v[212:215], v166 offset:22528
	ds_read_b128 v[216:219], v166 offset:23552
	global_load_lds_dwordx4 v140, s[30:31]
	s_add_i32 m0, s52, 0x2000
	s_add_u32 s52, s30, 0x100000
	s_addc_u32 s53, s31, 0
	s_add_i32 s54, s45, s36
	global_load_lds_dwordx4 v144, s[30:31]
	s_mov_b32 m0, s54
	s_nop 0
	global_load_lds_dwordx4 v140, s[52:53]
	s_add_i32 m0, s54, 0x2000
	s_nop 0
	global_load_lds_dwordx4 v144, s[52:53]
	s_waitcnt vmcnt(6)
	s_waitcnt lgkmcnt(0)
	s_setprio 1
	s_barrier
; #define PG8_STAGE(bufoff, gbase, voff) do { _Pragma("unroll") for (int _i = 0; _i < 2; ++_i) \
;         __builtin_amdgcn_global_load_lds((const unsigned*)((const char*)(gbase) + (voff)[_i]), (PG8_LAS unsigned*)(lds + (bufoff) + ldsw + _i * 8192), 16, 0, 0); } while (0)
; #define PG8_LDA(dst, b, h) do { _Pragma("unroll") for (int m = 0; m < 4; ++m) _Pragma("unroll") for (int k = 0; k < 2; ++k) dst[m][k] = *(const PG8_LAS bf16x8*)(lds + PG8_SA(b, h) + aoff + m * 2048 + k * 1024); } while (0)
; #define PG8_LDB(dst, b, h) do { _Pragma("unroll") for (int n = 0; n < 2; ++n) _Pragma("unroll") for (int k = 0; k < 2; ++k) dst[n][k] = *(const PG8_LAS bf16x8*)(lds + PG8_SB(b, h) + boff + n * 2048 + k * 1024); } while (0)
; #define PG8_MMA(ai, bj, At, Bt) do { __builtin_amdgcn_s_setprio(1); _Pragma("unroll") for (int m = 0; m < 4; ++m) _Pragma("unroll") for (int n = 0; n < 2; ++n) _Pragma("unroll") for (int k = 0; k < 2; ++k) \
;         acc[ai][bj][m][n] = __builtin_amdgcn_mfma_f32_16x16x32_bf16(Bt[n][k], At[m][k], acc[ai][bj][m][n], 0, 0, 0); __builtin_amdgcn_s_setprio(0); } while (0)
; #define PG8_WAIT_V(n) asm volatile("s_waitcnt vmcnt(" #n ")" ::: "memory")
; #define PG8_WAIT_L(n) asm volatile("s_waitcnt lgkmcnt(" #n ")" ::: "memory")
; #define PG8_BAR __builtin_amdgcn_s_barrier()
; #define PG8_SCHED __builtin_amdgcn_sched_barrier(0)
; template <class Epi, class Sched, bool ALIGN_EPI = false, bool SP2 = false>
; __device__ __forceinline__ void gemm_phase(PG8_LAS unsigned char* lds, const Gemm g, const Sched& S, const Epi& E) {
;     ...
;             PG8_WAIT_V(8); PG8_WAIT_L(0); PG8_BAR; PG8_MMA(0, 0, At, B0); PG8_MMA(0, 1, At, B1); PG8_BAR; PG8_SCHED;
;             PG8_LDA(At, 0, 1); PG8_STAGE(PG8_SB(0, 0), b2, voffB); PG8_STAGE(PG8_SB(0, 1), b2 + hstep, voffB); PG8_STAGE(PG8_SA(0, 0), a2, voffA);
;             PG8_WAIT_V(8); PG8_WAIT_L(0); PG8_BAR; PG8_MMA(1, 0, At, B0); PG8_MMA(1, 1, At, B1); PG8_BAR; PG8_SCHED;
;             PG8_LDB(B0, 1, 0); PG8_LDB(B1, 1, 1); PG8_SCHED; PG8_LDA(At, 1, 0); PG8_STAGE(PG8_SA(0, 1), a2 + hstep, voffA);
;             PG8_WAIT_V(8); PG8_WAIT_L(0); PG8_BAR; PG8_MMA(0, 0, At, B0); PG8_MMA(0, 1, At, B1); PG8_BAR; PG8_SCHED;
	v_mfma_f32_16x16x32_bf16 v[62:65], v[130:133], v[184:187], 0
	v_mfma_f32_16x16x32_bf16 v[58:61], v[154:157], v[184:187], 0
	v_mfma_f32_16x16x32_bf16 v[50:53], v[130:133], v[192:195], 0
	v_mfma_f32_16x16x32_bf16 v[42:45], v[154:157], v[192:195], 0
	v_mfma_f32_16x16x32_bf16 v[34:37], v[130:133], v[204:207], 0
	v_mfma_f32_16x16x32_bf16 v[26:29], v[154:157], v[204:207], 0
	v_mfma_f32_16x16x32_bf16 v[18:21], v[130:133], v[212:215], 0
	v_mfma_f32_16x16x32_bf16 v[10:13], v[154:157], v[212:215], 0
	v_mfma_f32_16x16x32_bf16 v[62:65], v[134:137], v[188:191], v[62:65]
	v_mfma_f32_16x16x32_bf16 v[58:61], v[158:161], v[188:191], v[58:61]
	v_mfma_f32_16x16x32_bf16 v[50:53], v[134:137], v[200:203], v[50:53]
	v_mfma_f32_16x16x32_bf16 v[42:45], v[158:161], v[200:203], v[42:45]
	v_mfma_f32_16x16x32_bf16 v[34:37], v[134:137], v[208:211], v[34:37]
	v_mfma_f32_16x16x32_bf16 v[26:29], v[158:161], v[208:211], v[26:29]
	v_mfma_f32_16x16x32_bf16 v[18:21], v[134:137], v[216:219], v[18:21]
	v_mfma_f32_16x16x32_bf16 v[10:13], v[158:161], v[216:219], v[10:13]
	v_mfma_f32_16x16x32_bf16 v[54:57], v[168:171], v[184:187], 0
	v_mfma_f32_16x16x32_bf16 v[46:49], v[176:179], v[184:187], 0
	v_mfma_f32_16x16x32_bf16 v[38:41], v[168:171], v[192:195], 0
	v_mfma_f32_16x16x32_bf16 v[30:33], v[176:179], v[192:195], 0
	v_mfma_f32_16x16x32_bf16 v[22:25], v[168:171], v[204:207], 0
	v_mfma_f32_16x16x32_bf16 v[14:17], v[176:179], v[204:207], 0
	v_mfma_f32_16x16x32_bf16 v[6:9], v[168:171], v[212:215], 0
	v_mfma_f32_16x16x32_bf16 v[2:5], v[176:179], v[212:215], 0
	v_mfma_f32_16x16x32_bf16 v[54:57], v[172:175], v[188:191], v[54:57]
	v_mfma_f32_16x16x32_bf16 v[46:49], v[180:183], v[188:191], v[46:49]
	v_mfma_f32_16x16x32_bf16 v[38:41], v[172:175], v[200:203], v[38:41]
	v_mfma_f32_16x16x32_bf16 v[30:33], v[180:183], v[200:203], v[30:33]
	v_mfma_f32_16x16x32_bf16 v[22:25], v[172:175], v[208:211], v[22:25]
	v_mfma_f32_16x16x32_bf16 v[14:17], v[180:183], v[208:211], v[14:17]
	v_mfma_f32_16x16x32_bf16 v[6:9], v[172:175], v[216:219], v[6:9]
	v_mfma_f32_16x16x32_bf16 v[2:5], v[180:183], v[216:219], v[2:5]
	s_barrier
	s_setprio 0
	s_mov_b32 m0, s27
	s_nop 0
	global_load_lds_dwordx4 v138, s[34:35]
	s_mov_b32 m0, s37
	s_nop 0
	global_load_lds_dwordx4 v142, s[34:35]
	s_add_i32 s52, 0, 0x18000
	s_add_i32 s53, 0, 0x1c000
	v_add_u32_e32 v158, s52, v162
	v_add_u32_e32 v167, s53, v162
	ds_read_b128 v[130:133], v158
	ds_read_b128 v[134:137], v158 offset:1024
	ds_read_b128 v[154:157], v158 offset:2048
	ds_read_b128 v[158:161], v158 offset:3072
	ds_read_b128 v[168:171], v167
	ds_read_b128 v[172:175], v167 offset:1024
	ds_read_b128 v[176:179], v167 offset:2048
	ds_read_b128 v[180:183], v167 offset:3072
	s_add_u32 s34, s34, 0x100000
	s_addc_u32 s35, s35, 0
	s_mov_b32 m0, s38
	ds_read_b128 v[184:187], v166 offset:32768
	ds_read_b128 v[188:191], v166 offset:33792
	ds_read_b128 v[192:195], v166 offset:34816
	ds_read_b128 v[200:203], v166 offset:35840
	ds_read_b128 v[204:207], v166 offset:36864
	ds_read_b128 v[208:211], v166 offset:37888
	ds_read_b128 v[212:215], v166 offset:38912
	ds_read_b128 v[216:219], v166 offset:39936
	global_load_lds_dwordx4 v138, s[34:35]
	s_mov_b32 m0, s39
	s_nop 0
	global_load_lds_dwordx4 v142, s[34:35]
	s_waitcnt vmcnt(8)
	s_waitcnt lgkmcnt(0)
	s_setprio 1
	s_barrier
; #define PG8_STAGE(bufoff, gbase, voff) do { _Pragma("unroll") for (int _i = 0; _i < 2; ++_i) \
;         __builtin_amdgcn_global_load_lds((const unsigned*)((const char*)(gbase) + (voff)[_i]), (PG8_LAS unsigned*)(lds + (bufoff) + ldsw + _i * 8192), 16, 0, 0); } while (0)
; #define PG8_LDA(dst, b, h) do { _Pragma("unroll") for (int m = 0; m < 4; ++m) _Pragma("unroll") for (int k = 0; k < 2; ++k) dst[m][k] = *(const PG8_LAS bf16x8*)(lds + PG8_SA(b, h) + aoff + m * 2048 + k * 1024); } while (0)
; #define PG8_MMA(ai, bj, At, Bt) do { __builtin_amdgcn_s_setprio(1); _Pragma("unroll") for (int m = 0; m < 4; ++m) _Pragma("unroll") for (int n = 0; n < 2; ++n) _Pragma("unroll") for (int k = 0; k < 2; ++k) \
;         acc[ai][bj][m][n] = __builtin_amdgcn_mfma_f32_16x16x32_bf16(Bt[n][k], At[m][k], acc[ai][bj][m][n], 0, 0, 0); __builtin_amdgcn_s_setprio(0); } while (0)
; #define PG8_WAIT_V(n) asm volatile("s_waitcnt vmcnt(" #n ")" ::: "memory")
; #define PG8_WAIT_L(n) asm volatile("s_waitcnt lgkmcnt(" #n ")" ::: "memory")
; #define PG8_BAR __builtin_amdgcn_s_barrier()
; #define PG8_SCHED __builtin_amdgcn_sched_barrier(0)
; template <class Epi, class Sched, bool ALIGN_EPI = false, bool SP2 = false>
; __device__ __forceinline__ void gemm_phase(PG8_LAS unsigned char* lds, const Gemm g, const Sched& S, const Epi& E) {
;     ...
;             PG8_WAIT_V(8); PG8_WAIT_L(0); PG8_BAR; PG8_MMA(0, 0, At, B0); PG8_MMA(0, 1, At, B1); PG8_BAR; PG8_SCHED;
;             PG8_LDA(At, 1, 1); PG8_STAGE(PG8_SB(1, 0), b3, voffB); PG8_STAGE(PG8_SB(1, 1), b3 + hstep, voffB); PG8_STAGE(PG8_SA(1, 0), a3, voffA);
;             PG8_WAIT_V(8); PG8_WAIT_L(0); PG8_BAR; PG8_MMA(1, 0, At, B0); PG8_MMA(1, 1, At, B1); PG8_BAR; PG8_SCHED;
	v_mfma_f32_16x16x32_bf16 v[126:129], v[130:133], v[184:187], v[126:129]
	v_mfma_f32_16x16x32_bf16 v[122:125], v[154:157], v[184:187], v[122:125]
	v_mfma_f32_16x16x32_bf16 v[118:121], v[130:133], v[192:195], v[118:121]
	v_mfma_f32_16x16x32_bf16 v[114:117], v[154:157], v[192:195], v[114:117]
	v_mfma_f32_16x16x32_bf16 v[110:113], v[130:133], v[204:207], v[110:113]
	v_mfma_f32_16x16x32_bf16 v[102:105], v[154:157], v[204:207], v[102:105]
	v_mfma_f32_16x16x32_bf16 v[82:85], v[130:133], v[212:215], v[82:85]
	v_mfma_f32_16x16x32_bf16 v[74:77], v[154:157], v[212:215], v[74:77]
	v_mfma_f32_16x16x32_bf16 v[126:129], v[134:137], v[188:191], v[126:129]
	v_mfma_f32_16x16x32_bf16 v[122:125], v[158:161], v[188:191], v[122:125]
	v_mfma_f32_16x16x32_bf16 v[118:121], v[134:137], v[200:203], v[118:121]
	v_mfma_f32_16x16x32_bf16 v[114:117], v[158:161], v[200:203], v[114:117]
	v_mfma_f32_16x16x32_bf16 v[110:113], v[134:137], v[208:211], v[110:113]
	v_mfma_f32_16x16x32_bf16 v[102:105], v[158:161], v[208:211], v[102:105]
	v_mfma_f32_16x16x32_bf16 v[82:85], v[134:137], v[216:219], v[82:85]
	v_mfma_f32_16x16x32_bf16 v[74:77], v[158:161], v[216:219], v[74:77]
	v_mfma_f32_16x16x32_bf16 v[106:109], v[168:171], v[184:187], v[106:109]
	v_mfma_f32_16x16x32_bf16 v[98:101], v[176:179], v[184:187], v[98:101]
	v_mfma_f32_16x16x32_bf16 v[94:97], v[168:171], v[192:195], v[94:97]
	v_mfma_f32_16x16x32_bf16 v[90:93], v[176:179], v[192:195], v[90:93]
	v_mfma_f32_16x16x32_bf16 v[86:89], v[168:171], v[204:207], v[86:89]
	v_mfma_f32_16x16x32_bf16 v[78:81], v[176:179], v[204:207], v[78:81]
	v_mfma_f32_16x16x32_bf16 v[70:73], v[168:171], v[212:215], v[70:73]
	v_mfma_f32_16x16x32_bf16 v[66:69], v[176:179], v[212:215], v[66:69]
	v_mfma_f32_16x16x32_bf16 v[106:109], v[172:175], v[188:191], v[106:109]
	v_mfma_f32_16x16x32_bf16 v[98:101], v[180:183], v[188:191], v[98:101]
	v_mfma_f32_16x16x32_bf16 v[94:97], v[172:175], v[200:203], v[94:97]
	v_mfma_f32_16x16x32_bf16 v[90:93], v[180:183], v[200:203], v[90:93]
	v_mfma_f32_16x16x32_bf16 v[86:89], v[172:175], v[208:211], v[86:89]
	v_mfma_f32_16x16x32_bf16 v[78:81], v[180:183], v[208:211], v[78:81]
	v_mfma_f32_16x16x32_bf16 v[70:73], v[172:175], v[216:219], v[70:73]
	v_mfma_f32_16x16x32_bf16 v[66:69], v[180:183], v[216:219], v[66:69]
	s_barrier
	s_setprio 0
	s_add_i32 s34, s52, s36
	s_add_u32 s30, s30, 0x80
	s_addc_u32 s31, s31, 0
	s_mov_b32 m0, s34
	ds_read_b128 v[184:187], v166 offset:49152
	ds_read_b128 v[188:191], v166 offset:50176
	ds_read_b128 v[192:195], v166 offset:51200
	ds_read_b128 v[200:203], v166 offset:52224
	ds_read_b128 v[204:207], v166 offset:53248
	ds_read_b128 v[208:211], v166 offset:54272
	ds_read_b128 v[212:215], v166 offset:55296
	ds_read_b128 v[216:219], v166 offset:56320
	global_load_lds_dwordx4 v140, s[30:31]
	s_add_i32 m0, s34, 0x2000
	s_add_i32 s34, s53, s36
	global_load_lds_dwordx4 v144, s[30:31]
	s_add_u32 s30, s30, 0x100000
	s_addc_u32 s31, s31, 0
	s_mov_b32 m0, s34
	s_nop 0
	global_load_lds_dwordx4 v140, s[30:31]
	s_add_i32 m0, s34, 0x2000
	s_nop 0
	global_load_lds_dwordx4 v144, s[30:31]
	s_waitcnt vmcnt(6)
	s_waitcnt lgkmcnt(0)
	s_setprio 1
	s_barrier
	v_mfma_f32_16x16x32_bf16 v[62:65], v[130:133], v[184:187], v[62:65]
	v_mfma_f32_16x16x32_bf16 v[58:61], v[154:157], v[184:187], v[58:61]
	v_mfma_f32_16x16x32_bf16 v[50:53], v[130:133], v[192:195], v[50:53]
	v_mfma_f32_16x16x32_bf16 v[42:45], v[154:157], v[192:195], v[42:45]
	v_mfma_f32_16x16x32_bf16 v[34:37], v[130:133], v[204:207], v[34:37]
	v_mfma_f32_16x16x32_bf16 v[26:29], v[154:157], v[204:207], v[26:29]
	v_mfma_f32_16x16x32_bf16 v[18:21], v[130:133], v[212:215], v[18:21]
	v_mfma_f32_16x16x32_bf16 v[10:13], v[154:157], v[212:215], v[10:13]
	v_mfma_f32_16x16x32_bf16 v[62:65], v[134:137], v[188:191], v[62:65]
	v_mfma_f32_16x16x32_bf16 v[58:61], v[158:161], v[188:191], v[58:61]
	v_mfma_f32_16x16x32_bf16 v[50:53], v[134:137], v[200:203], v[50:53]
	v_mfma_f32_16x16x32_bf16 v[42:45], v[158:161], v[200:203], v[42:45]
	v_mfma_f32_16x16x32_bf16 v[34:37], v[134:137], v[208:211], v[34:37]
	v_mfma_f32_16x16x32_bf16 v[26:29], v[158:161], v[208:211], v[26:29]
	v_mfma_f32_16x16x32_bf16 v[18:21], v[134:137], v[216:219], v[18:21]
	v_mfma_f32_16x16x32_bf16 v[10:13], v[158:161], v[216:219], v[10:13]
	v_mfma_f32_16x16x32_bf16 v[54:57], v[168:171], v[184:187], v[54:57]
	v_mfma_f32_16x16x32_bf16 v[46:49], v[176:179], v[184:187], v[46:49]
	v_mfma_f32_16x16x32_bf16 v[38:41], v[168:171], v[192:195], v[38:41]
	v_mfma_f32_16x16x32_bf16 v[30:33], v[176:179], v[192:195], v[30:33]
	v_mfma_f32_16x16x32_bf16 v[22:25], v[168:171], v[204:207], v[22:25]
	v_mfma_f32_16x16x32_bf16 v[14:17], v[176:179], v[204:207], v[14:17]
	v_mfma_f32_16x16x32_bf16 v[6:9], v[168:171], v[212:215], v[6:9]
	v_mfma_f32_16x16x32_bf16 v[2:5], v[176:179], v[212:215], v[2:5]
	v_mfma_f32_16x16x32_bf16 v[54:57], v[172:175], v[188:191], v[54:57]
	v_mfma_f32_16x16x32_bf16 v[46:49], v[180:183], v[188:191], v[46:49]
	v_mfma_f32_16x16x32_bf16 v[38:41], v[172:175], v[200:203], v[38:41]
	v_mfma_f32_16x16x32_bf16 v[30:33], v[180:183], v[200:203], v[30:33]
	v_mfma_f32_16x16x32_bf16 v[22:25], v[172:175], v[208:211], v[22:25]
	v_mfma_f32_16x16x32_bf16 v[14:17], v[180:183], v[208:211], v[14:17]
	v_mfma_f32_16x16x32_bf16 v[6:9], v[172:175], v[216:219], v[6:9]
	v_mfma_f32_16x16x32_bf16 v[2:5], v[180:183], v[216:219], v[2:5]
	s_barrier
	s_setprio 0
	s_add_i32 s51, s51, 2
	s_add_u32 s28, s28, 0x100
	s_addc_u32 s29, s29, 0
	s_add_u32 s49, s49, 0x100
	s_addc_u32 s50, s50, 0
	s_cmp_gt_u32 s51, 61
	.p2align 8

; #define PG8_STAGE(bufoff, gbase, voff) do { _Pragma("unroll") for (int _i = 0; _i < 2; ++_i) \
;         __builtin_amdgcn_global_load_lds((const unsigned*)((const char*)(gbase) + (voff)[_i]), (PG8_LAS unsigned*)(lds + (bufoff) + ldsw + _i * 8192), 16, 0, 0); } while (0)
; #define PG8_LDA(dst, b, h) do { _Pragma("unroll") for (int m = 0; m < 4; ++m) _Pragma("unroll") for (int k = 0; k < 2; ++k) dst[m][k] = *(const PG8_LAS bf16x8*)(lds + PG8_SA(b, h) + aoff + m * 2048 + k * 1024); } while (0)
; #define PG8_LDB(dst, b, h) do { _Pragma("unroll") for (int n = 0; n < 2; ++n) _Pragma("unroll") for (int k = 0; k < 2; ++k) dst[n][k] = *(const PG8_LAS bf16x8*)(lds + PG8_SB(b, h) + boff + n * 2048 + k * 1024); } while (0)
; #define PG8_WAIT_V(n) asm volatile("s_waitcnt vmcnt(" #n ")" ::: "memory")
; #define PG8_WAIT_L(n) asm volatile("s_waitcnt lgkmcnt(" #n ")" ::: "memory")
; #define PG8_BAR __builtin_amdgcn_s_barrier()
; #define PG8_SCHED __builtin_amdgcn_sched_barrier(0)
; template <class Epi, class Sched, bool ALIGN_EPI = false, bool SP2 = false>
; __device__ __forceinline__ void gemm_phase(PG8_LAS unsigned char* lds, const Gemm g, const Sched& S, const Epi& E) {
;     ...
;         const bool has_next = S.next(ui + 1, nxt);
;         const char* nA = has_next ? (const char*)g.A + (size_t)nxt.pm * tstep : cA; const char* nB = has_next ? (const char*)g.Bt + (size_t)nxt.pn * tstep : cB;
;         for (int t = 0; t < nt; t += 2) {
;             const bool last = (t == nt - 2);
;             const char* a1 = cA + (size_t)(t + 1) * kstep;
;             const char* a2 = last ? nA : cA + (size_t)(t + 2) * kstep; const char* b2 = last ? nB : cB + (size_t)(t + 2) * kstep;
;             const char* a3 = a2 + kstep; const char* b3 = b2 + kstep;
;             if (last && has_next) S.a_ready(nxt);
;             if constexpr (SP2) {
;             PG8_LDB(B0, 0, 0); PG8_LDB(B1, 0, 1); PG8_SCHED; PG8_LDA(At, 0, 0); PG8_STAGE(PG8_SA(1, 1), a1 + hstep, voffA);
;             PG8_WAIT_V(8); PG8_WAIT_L(0); PG8_BAR; PG8_MMA(0, 0, At, B0); PG8_MMA(0, 1, At, B1); PG8_BAR; PG8_SCHED;
;             PG8_LDA(At, 0, 1); PG8_STAGE(PG8_SB(0, 0), b2, voffB); PG8_STAGE(PG8_SB(0, 1), b2 + hstep, voffB); PG8_STAGE(PG8_SA(0, 0), a2, voffA);
;             PG8_WAIT_V(8); PG8_WAIT_L(0); PG8_BAR; PG8_MMA(1, 0, At, B0); PG8_MMA(1, 1, At, B1); PG8_BAR; PG8_SCHED;
.LBB0_1080:
	s_ashr_i32 s15, s14, 31
	s_lshl_b64 s[24:25], s[14:15], 21
	s_add_u32 s24, s86, s24
	s_addc_u32 s25, s87, s25
	s_and_b64 s[26:27], s[0:1], exec
	s_cselect_b32 s15, s25, s31
	s_cselect_b32 s51, s24, s30
	s_ashr_i32 s13, s12, 31
	s_lshl_b64 s[26:27], s[12:13], 21
	v_readlane_b32 s36, v254, 29
	v_readlane_b32 s37, v254, 30
	s_add_u32 s26, s36, s26
	s_addc_u32 s27, s37, s27
	s_and_b64 s[36:37], s[0:1], exec
	s_cselect_b32 s13, s27, s35
	s_cselect_b32 s52, s26, s34
	s_add_u32 s30, s30, 0x100080
	s_addc_u32 s31, s31, 0
	s_add_u32 s53, s34, 0x100
	s_addc_u32 s54, s35, 0
	s_mov_b32 s55, -2
	s_add_u32 s34, s30, 0xfff00000
	s_addc_u32 s35, s31, -1
	s_mov_b32 m0, s44
	s_nop 0
	global_load_lds_dwordx4 v136, s[34:35]
	s_mov_b32 m0, s45
	s_nop 0
	global_load_lds_dwordx4 v132, s[34:35]
	s_add_u32 s34, s34, 0x80
	s_addc_u32 s35, s35, 0
	ds_read_b128 v[154:157], v150
	ds_read_b128 v[158:161], v150 offset:1024
	ds_read_b128 v[162:165], v150 offset:2048
	ds_read_b128 v[166:169], v150 offset:3072
	ds_read_b128 v[170:173], v151
	ds_read_b128 v[174:177], v151 offset:1024
	ds_read_b128 v[178:181], v151 offset:2048
	ds_read_b128 v[182:185], v151 offset:3072
	s_cmp_eq_u32 s55, 60
	s_cselect_b32 s37, s15, s35
	s_cselect_b32 s36, s51, s34
	s_cselect_b32 s35, s13, s54
	s_cselect_b32 s34, s52, s53
	s_add_i32 m0, s29, 0xc000
	ds_read_b128 v[186:189], v152
	ds_read_b128 v[190:193], v152 offset:1024
	ds_read_b128 v[194:197], v152 offset:2048
	ds_read_b128 v[200:203], v152 offset:3072
	ds_read_b128 v[204:207], v152 offset:4096
	ds_read_b128 v[208:211], v152 offset:5120
	ds_read_b128 v[212:215], v152 offset:6144
	ds_read_b128 v[216:219], v152 offset:7168
	global_load_lds_dwordx4 v138, s[30:31]
	s_add_i32 m0, s29, 0xe000
	s_nop 0
	global_load_lds_dwordx4 v140, s[30:31]
	s_waitcnt vmcnt(8)
	s_waitcnt lgkmcnt(0)
	s_setprio 1
	s_barrier
	v_mfma_f32_16x16x32_bf16 v[126:129], v[154:157], v[186:189], 0
	v_mfma_f32_16x16x32_bf16 v[122:125], v[162:165], v[186:189], 0
	v_mfma_f32_16x16x32_bf16 v[110:113], v[154:157], v[194:197], 0
	v_mfma_f32_16x16x32_bf16 v[106:109], v[162:165], v[194:197], 0
	v_mfma_f32_16x16x32_bf16 v[94:97], v[154:157], v[204:207], 0
	v_mfma_f32_16x16x32_bf16 v[90:93], v[162:165], v[204:207], 0
	v_mfma_f32_16x16x32_bf16 v[78:81], v[154:157], v[212:215], 0
	v_mfma_f32_16x16x32_bf16 v[74:77], v[162:165], v[212:215], 0
	v_mfma_f32_16x16x32_bf16 v[126:129], v[158:161], v[190:193], v[126:129]
	v_mfma_f32_16x16x32_bf16 v[122:125], v[166:169], v[190:193], v[122:125]
	v_mfma_f32_16x16x32_bf16 v[110:113], v[158:161], v[200:203], v[110:113]
	v_mfma_f32_16x16x32_bf16 v[106:109], v[166:169], v[200:203], v[106:109]
	v_mfma_f32_16x16x32_bf16 v[94:97], v[158:161], v[208:211], v[94:97]
	v_mfma_f32_16x16x32_bf16 v[90:93], v[166:169], v[208:211], v[90:93]
	v_mfma_f32_16x16x32_bf16 v[78:81], v[158:161], v[216:219], v[78:81]
	v_mfma_f32_16x16x32_bf16 v[74:77], v[166:169], v[216:219], v[74:77]
	v_mfma_f32_16x16x32_bf16 v[118:121], v[170:173], v[186:189], 0
	v_mfma_f32_16x16x32_bf16 v[114:117], v[178:181], v[186:189], 0
	v_mfma_f32_16x16x32_bf16 v[102:105], v[170:173], v[194:197], 0
	v_mfma_f32_16x16x32_bf16 v[98:101], v[178:181], v[194:197], 0
	v_mfma_f32_16x16x32_bf16 v[86:89], v[170:173], v[204:207], 0
	v_mfma_f32_16x16x32_bf16 v[82:85], v[178:181], v[204:207], 0
	v_mfma_f32_16x16x32_bf16 v[70:73], v[170:173], v[212:215], 0
	v_mfma_f32_16x16x32_bf16 v[66:69], v[178:181], v[212:215], 0
	v_mfma_f32_16x16x32_bf16 v[118:121], v[174:177], v[190:193], v[118:121]
	v_mfma_f32_16x16x32_bf16 v[114:117], v[182:185], v[190:193], v[114:117]
	v_mfma_f32_16x16x32_bf16 v[102:105], v[174:177], v[200:203], v[102:105]
	v_mfma_f32_16x16x32_bf16 v[98:101], v[182:185], v[200:203], v[98:101]
	v_mfma_f32_16x16x32_bf16 v[86:89], v[174:177], v[208:211], v[86:89]
	v_mfma_f32_16x16x32_bf16 v[82:85], v[182:185], v[208:211], v[82:85]
	v_mfma_f32_16x16x32_bf16 v[70:73], v[174:177], v[216:219], v[70:73]
	v_mfma_f32_16x16x32_bf16 v[66:69], v[182:185], v[216:219], v[66:69]
	s_barrier
	s_setprio 0
	s_add_i32 s56, s47, s33
	s_mov_b32 m0, s56
	ds_read_b128 v[186:189], v152 offset:16384
	ds_read_b128 v[190:193], v152 offset:17408
	ds_read_b128 v[194:197], v152 offset:18432
	ds_read_b128 v[200:203], v152 offset:19456
	ds_read_b128 v[204:207], v152 offset:20480
	ds_read_b128 v[208:211], v152 offset:21504
	ds_read_b128 v[212:215], v152 offset:22528
	ds_read_b128 v[216:219], v152 offset:23552
	global_load_lds_dwordx4 v134, s[34:35]
	s_add_i32 m0, s56, 0x2000
	s_add_u32 s56, s34, 0x100000
	s_addc_u32 s57, s35, 0
	s_add_i32 s58, s48, s33
	global_load_lds_dwordx4 v130, s[34:35]
	s_mov_b32 m0, s58
	s_nop 0
	global_load_lds_dwordx4 v134, s[56:57]
	s_add_i32 m0, s58, 0x2000
	s_nop 0
	global_load_lds_dwordx4 v130, s[56:57]
	s_waitcnt vmcnt(6)
	s_waitcnt lgkmcnt(0)
	s_setprio 1
	s_barrier
; #define PG8_STAGE(bufoff, gbase, voff) do { _Pragma("unroll") for (int _i = 0; _i < 2; ++_i) \
;         __builtin_amdgcn_global_load_lds((const unsigned*)((const char*)(gbase) + (voff)[_i]), (PG8_LAS unsigned*)(lds + (bufoff) + ldsw + _i * 8192), 16, 0, 0); } while (0)
; #define PG8_LDA(dst, b, h) do { _Pragma("unroll") for (int m = 0; m < 4; ++m) _Pragma("unroll") for (int k = 0; k < 2; ++k) dst[m][k] = *(const PG8_LAS bf16x8*)(lds + PG8_SA(b, h) + aoff + m * 2048 + k * 1024); } while (0)
; #define PG8_LDB(dst, b, h) do { _Pragma("unroll") for (int n = 0; n < 2; ++n) _Pragma("unroll") for (int k = 0; k < 2; ++k) dst[n][k] = *(const PG8_LAS bf16x8*)(lds + PG8_SB(b, h) + boff + n * 2048 + k * 1024); } while (0)
; #define PG8_MMA(ai, bj, At, Bt) do { __builtin_amdgcn_s_setprio(1); _Pragma("unroll") for (int m = 0; m < 4; ++m) _Pragma("unroll") for (int n = 0; n < 2; ++n) _Pragma("unroll") for (int k = 0; k < 2; ++k) \
;         acc[ai][bj][m][n] = __builtin_amdgcn_mfma_f32_16x16x32_bf16(Bt[n][k], At[m][k], acc[ai][bj][m][n], 0, 0, 0); __builtin_amdgcn_s_setprio(0); } while (0)
; #define PG8_WAIT_V(n) asm volatile("s_waitcnt vmcnt(" #n ")" ::: "memory")
; #define PG8_WAIT_L(n) asm volatile("s_waitcnt lgkmcnt(" #n ")" ::: "memory")
; #define PG8_BAR __builtin_amdgcn_s_barrier()
; #define PG8_SCHED __builtin_amdgcn_sched_barrier(0)
; template <class Epi, class Sched, bool ALIGN_EPI = false, bool SP2 = false>
; __device__ __forceinline__ void gemm_phase(PG8_LAS unsigned char* lds, const Gemm g, const Sched& S, const Epi& E) {
;     ...
;             PG8_WAIT_V(8); PG8_WAIT_L(0); PG8_BAR; PG8_MMA(0, 0, At, B0); PG8_MMA(0, 1, At, B1); PG8_BAR; PG8_SCHED;
;             PG8_LDA(At, 0, 1); PG8_STAGE(PG8_SB(0, 0), b2, voffB); PG8_STAGE(PG8_SB(0, 1), b2 + hstep, voffB); PG8_STAGE(PG8_SA(0, 0), a2, voffA);
;             PG8_WAIT_V(8); PG8_WAIT_L(0); PG8_BAR; PG8_MMA(1, 0, At, B0); PG8_MMA(1, 1, At, B1); PG8_BAR; PG8_SCHED;
;             PG8_LDB(B0, 1, 0); PG8_LDB(B1, 1, 1); PG8_SCHED; PG8_LDA(At, 1, 0); PG8_STAGE(PG8_SA(0, 1), a2 + hstep, voffA);
;             PG8_WAIT_V(8); PG8_WAIT_L(0); PG8_BAR; PG8_MMA(0, 0, At, B0); PG8_MMA(0, 1, At, B1); PG8_BAR; PG8_SCHED;
	v_mfma_f32_16x16x32_bf16 v[62:65], v[154:157], v[186:189], 0
	v_mfma_f32_16x16x32_bf16 v[58:61], v[162:165], v[186:189], 0
	v_mfma_f32_16x16x32_bf16 v[46:49], v[154:157], v[194:197], 0
	v_mfma_f32_16x16x32_bf16 v[42:45], v[162:165], v[194:197], 0
	v_mfma_f32_16x16x32_bf16 v[30:33], v[154:157], v[204:207], 0
	v_mfma_f32_16x16x32_bf16 v[26:29], v[162:165], v[204:207], 0
	v_mfma_f32_16x16x32_bf16 v[14:17], v[154:157], v[212:215], 0
	v_mfma_f32_16x16x32_bf16 v[10:13], v[162:165], v[212:215], 0
	v_mfma_f32_16x16x32_bf16 v[62:65], v[158:161], v[190:193], v[62:65]
	v_mfma_f32_16x16x32_bf16 v[58:61], v[166:169], v[190:193], v[58:61]
	v_mfma_f32_16x16x32_bf16 v[46:49], v[158:161], v[200:203], v[46:49]
	v_mfma_f32_16x16x32_bf16 v[42:45], v[166:169], v[200:203], v[42:45]
	v_mfma_f32_16x16x32_bf16 v[30:33], v[158:161], v[208:211], v[30:33]
	v_mfma_f32_16x16x32_bf16 v[26:29], v[166:169], v[208:211], v[26:29]
	v_mfma_f32_16x16x32_bf16 v[14:17], v[158:161], v[216:219], v[14:17]
	v_mfma_f32_16x16x32_bf16 v[10:13], v[166:169], v[216:219], v[10:13]
	v_mfma_f32_16x16x32_bf16 v[54:57], v[170:173], v[186:189], 0
	v_mfma_f32_16x16x32_bf16 v[50:53], v[178:181], v[186:189], 0
	v_mfma_f32_16x16x32_bf16 v[38:41], v[170:173], v[194:197], 0
	v_mfma_f32_16x16x32_bf16 v[34:37], v[178:181], v[194:197], 0
	v_mfma_f32_16x16x32_bf16 v[22:25], v[170:173], v[204:207], 0
	v_mfma_f32_16x16x32_bf16 v[18:21], v[178:181], v[204:207], 0
	v_mfma_f32_16x16x32_bf16 v[6:9], v[170:173], v[212:215], 0
	v_mfma_f32_16x16x32_bf16 v[2:5], v[178:181], v[212:215], 0
	v_mfma_f32_16x16x32_bf16 v[54:57], v[174:177], v[190:193], v[54:57]
	v_mfma_f32_16x16x32_bf16 v[50:53], v[182:185], v[190:193], v[50:53]
	v_mfma_f32_16x16x32_bf16 v[38:41], v[174:177], v[200:203], v[38:41]
	v_mfma_f32_16x16x32_bf16 v[34:37], v[182:185], v[200:203], v[34:37]
	v_mfma_f32_16x16x32_bf16 v[22:25], v[174:177], v[208:211], v[22:25]
	v_mfma_f32_16x16x32_bf16 v[18:21], v[182:185], v[208:211], v[18:21]
	v_mfma_f32_16x16x32_bf16 v[6:9], v[174:177], v[216:219], v[6:9]
	v_mfma_f32_16x16x32_bf16 v[2:5], v[182:185], v[216:219], v[2:5]
	s_barrier
	s_setprio 0
	s_mov_b32 m0, s29
	s_nop 0
	global_load_lds_dwordx4 v136, s[36:37]
	s_mov_b32 m0, s40
	s_nop 0
	global_load_lds_dwordx4 v132, s[36:37]
	s_add_i32 s56, 0, 0x18000
	v_add_u32_e32 v153, s56, v148
	s_add_i32 s57, 0, 0x1c000
	ds_read_b128 v[154:157], v153
	ds_read_b128 v[158:161], v153 offset:1024
	ds_read_b128 v[162:165], v153 offset:2048
	ds_read_b128 v[166:169], v153 offset:3072
	v_add_u32_e32 v153, s57, v148
	ds_read_b128 v[170:173], v153
	ds_read_b128 v[174:177], v153 offset:1024
	ds_read_b128 v[178:181], v153 offset:2048
	ds_read_b128 v[182:185], v153 offset:3072
	s_add_u32 s36, s36, 0x100000
	s_addc_u32 s37, s37, 0
	s_mov_b32 m0, s41
	ds_read_b128 v[186:189], v152 offset:32768
	ds_read_b128 v[190:193], v152 offset:33792
	ds_read_b128 v[194:197], v152 offset:34816
	ds_read_b128 v[200:203], v152 offset:35840
	ds_read_b128 v[204:207], v152 offset:36864
	ds_read_b128 v[208:211], v152 offset:37888
	ds_read_b128 v[212:215], v152 offset:38912
	ds_read_b128 v[216:219], v152 offset:39936
	global_load_lds_dwordx4 v136, s[36:37]
	s_mov_b32 m0, s42
	s_nop 0
	global_load_lds_dwordx4 v132, s[36:37]
	s_waitcnt vmcnt(8)
	s_waitcnt lgkmcnt(0)
	s_setprio 1
	s_barrier
; #define PG8_STAGE(bufoff, gbase, voff) do { _Pragma("unroll") for (int _i = 0; _i < 2; ++_i) \
;         __builtin_amdgcn_global_load_lds((const unsigned*)((const char*)(gbase) + (voff)[_i]), (PG8_LAS unsigned*)(lds + (bufoff) + ldsw + _i * 8192), 16, 0, 0); } while (0)
; #define PG8_LDA(dst, b, h) do { _Pragma("unroll") for (int m = 0; m < 4; ++m) _Pragma("unroll") for (int k = 0; k < 2; ++k) dst[m][k] = *(const PG8_LAS bf16x8*)(lds + PG8_SA(b, h) + aoff + m * 2048 + k * 1024); } while (0)
; #define PG8_MMA(ai, bj, At, Bt) do { __builtin_amdgcn_s_setprio(1); _Pragma("unroll") for (int m = 0; m < 4; ++m) _Pragma("unroll") for (int n = 0; n < 2; ++n) _Pragma("unroll") for (int k = 0; k < 2; ++k) \
;         acc[ai][bj][m][n] = __builtin_amdgcn_mfma_f32_16x16x32_bf16(Bt[n][k], At[m][k], acc[ai][bj][m][n], 0, 0, 0); __builtin_amdgcn_s_setprio(0); } while (0)
; #define PG8_WAIT_V(n) asm volatile("s_waitcnt vmcnt(" #n ")" ::: "memory")
; #define PG8_WAIT_L(n) asm volatile("s_waitcnt lgkmcnt(" #n ")" ::: "memory")
; #define PG8_BAR __builtin_amdgcn_s_barrier()
; #define PG8_SCHED __builtin_amdgcn_sched_barrier(0)
; template <class Epi, class Sched, bool ALIGN_EPI = false, bool SP2 = false>
; __device__ __forceinline__ void gemm_phase(PG8_LAS unsigned char* lds, const Gemm g, const Sched& S, const Epi& E) {
;     ...
;             PG8_WAIT_V(8); PG8_WAIT_L(0); PG8_BAR; PG8_MMA(0, 0, At, B0); PG8_MMA(0, 1, At, B1); PG8_BAR; PG8_SCHED;
;             PG8_LDA(At, 1, 1); PG8_STAGE(PG8_SB(1, 0), b3, voffB); PG8_STAGE(PG8_SB(1, 1), b3 + hstep, voffB); PG8_STAGE(PG8_SA(1, 0), a3, voffA);
;             PG8_WAIT_V(8); PG8_WAIT_L(0); PG8_BAR; PG8_MMA(1, 0, At, B0); PG8_MMA(1, 1, At, B1); PG8_BAR; PG8_SCHED;
	v_mfma_f32_16x16x32_bf16 v[126:129], v[154:157], v[186:189], v[126:129]
	v_mfma_f32_16x16x32_bf16 v[122:125], v[162:165], v[186:189], v[122:125]
	v_mfma_f32_16x16x32_bf16 v[110:113], v[154:157], v[194:197], v[110:113]
	v_mfma_f32_16x16x32_bf16 v[106:109], v[162:165], v[194:197], v[106:109]
	v_mfma_f32_16x16x32_bf16 v[94:97], v[154:157], v[204:207], v[94:97]
	v_mfma_f32_16x16x32_bf16 v[90:93], v[162:165], v[204:207], v[90:93]
	v_mfma_f32_16x16x32_bf16 v[78:81], v[154:157], v[212:215], v[78:81]
	v_mfma_f32_16x16x32_bf16 v[74:77], v[162:165], v[212:215], v[74:77]
	v_mfma_f32_16x16x32_bf16 v[126:129], v[158:161], v[190:193], v[126:129]
	v_mfma_f32_16x16x32_bf16 v[122:125], v[166:169], v[190:193], v[122:125]
	v_mfma_f32_16x16x32_bf16 v[110:113], v[158:161], v[200:203], v[110:113]
	v_mfma_f32_16x16x32_bf16 v[106:109], v[166:169], v[200:203], v[106:109]
	v_mfma_f32_16x16x32_bf16 v[94:97], v[158:161], v[208:211], v[94:97]
	v_mfma_f32_16x16x32_bf16 v[90:93], v[166:169], v[208:211], v[90:93]
	v_mfma_f32_16x16x32_bf16 v[78:81], v[158:161], v[216:219], v[78:81]
	v_mfma_f32_16x16x32_bf16 v[74:77], v[166:169], v[216:219], v[74:77]
	v_mfma_f32_16x16x32_bf16 v[118:121], v[170:173], v[186:189], v[118:121]
	v_mfma_f32_16x16x32_bf16 v[114:117], v[178:181], v[186:189], v[114:117]
	v_mfma_f32_16x16x32_bf16 v[102:105], v[170:173], v[194:197], v[102:105]
	v_mfma_f32_16x16x32_bf16 v[98:101], v[178:181], v[194:197], v[98:101]
	v_mfma_f32_16x16x32_bf16 v[86:89], v[170:173], v[204:207], v[86:89]
	v_mfma_f32_16x16x32_bf16 v[82:85], v[178:181], v[204:207], v[82:85]
	v_mfma_f32_16x16x32_bf16 v[70:73], v[170:173], v[212:215], v[70:73]
	v_mfma_f32_16x16x32_bf16 v[66:69], v[178:181], v[212:215], v[66:69]
	v_mfma_f32_16x16x32_bf16 v[118:121], v[174:177], v[190:193], v[118:121]
	v_mfma_f32_16x16x32_bf16 v[114:117], v[182:185], v[190:193], v[114:117]
	v_mfma_f32_16x16x32_bf16 v[102:105], v[174:177], v[200:203], v[102:105]
	v_mfma_f32_16x16x32_bf16 v[98:101], v[182:185], v[200:203], v[98:101]
	v_mfma_f32_16x16x32_bf16 v[86:89], v[174:177], v[208:211], v[86:89]
	v_mfma_f32_16x16x32_bf16 v[82:85], v[182:185], v[208:211], v[82:85]
	v_mfma_f32_16x16x32_bf16 v[70:73], v[174:177], v[216:219], v[70:73]
	v_mfma_f32_16x16x32_bf16 v[66:69], v[182:185], v[216:219], v[66:69]
	s_barrier
	s_setprio 0
	s_add_i32 s36, s56, s33
	s_add_u32 s34, s34, 0x80
	s_addc_u32 s35, s35, 0
	s_mov_b32 m0, s36
	ds_read_b128 v[186:189], v152 offset:49152
	ds_read_b128 v[190:193], v152 offset:50176
	ds_read_b128 v[194:197], v152 offset:51200
	ds_read_b128 v[200:203], v152 offset:52224
	ds_read_b128 v[204:207], v152 offset:53248
	ds_read_b128 v[208:211], v152 offset:54272
	ds_read_b128 v[212:215], v152 offset:55296
	ds_read_b128 v[216:219], v152 offset:56320
	global_load_lds_dwordx4 v134, s[34:35]
	s_add_i32 m0, s36, 0x2000
	s_add_i32 s36, s57, s33
	global_load_lds_dwordx4 v130, s[34:35]
	s_add_u32 s34, s34, 0x100000
	s_addc_u32 s35, s35, 0
	s_mov_b32 m0, s36
	s_nop 0
	global_load_lds_dwordx4 v134, s[34:35]
	s_add_i32 m0, s36, 0x2000
	s_nop 0
	global_load_lds_dwordx4 v130, s[34:35]
	s_waitcnt vmcnt(6)
	s_waitcnt lgkmcnt(0)
	s_setprio 1
	s_barrier
	v_mfma_f32_16x16x32_bf16 v[62:65], v[154:157], v[186:189], v[62:65]
	v_mfma_f32_16x16x32_bf16 v[58:61], v[162:165], v[186:189], v[58:61]
	v_mfma_f32_16x16x32_bf16 v[46:49], v[154:157], v[194:197], v[46:49]
	v_mfma_f32_16x16x32_bf16 v[42:45], v[162:165], v[194:197], v[42:45]
	v_mfma_f32_16x16x32_bf16 v[30:33], v[154:157], v[204:207], v[30:33]
	v_mfma_f32_16x16x32_bf16 v[26:29], v[162:165], v[204:207], v[26:29]
	v_mfma_f32_16x16x32_bf16 v[14:17], v[154:157], v[212:215], v[14:17]
	v_mfma_f32_16x16x32_bf16 v[10:13], v[162:165], v[212:215], v[10:13]
	v_mfma_f32_16x16x32_bf16 v[62:65], v[158:161], v[190:193], v[62:65]
	v_mfma_f32_16x16x32_bf16 v[58:61], v[166:169], v[190:193], v[58:61]
	v_mfma_f32_16x16x32_bf16 v[46:49], v[158:161], v[200:203], v[46:49]
	v_mfma_f32_16x16x32_bf16 v[42:45], v[166:169], v[200:203], v[42:45]
	v_mfma_f32_16x16x32_bf16 v[30:33], v[158:161], v[208:211], v[30:33]
	v_mfma_f32_16x16x32_bf16 v[26:29], v[166:169], v[208:211], v[26:29]
	v_mfma_f32_16x16x32_bf16 v[14:17], v[158:161], v[216:219], v[14:17]
	v_mfma_f32_16x16x32_bf16 v[10:13], v[166:169], v[216:219], v[10:13]
	v_mfma_f32_16x16x32_bf16 v[54:57], v[170:173], v[186:189], v[54:57]
	v_mfma_f32_16x16x32_bf16 v[50:53], v[178:181], v[186:189], v[50:53]
	v_mfma_f32_16x16x32_bf16 v[38:41], v[170:173], v[194:197], v[38:41]
	v_mfma_f32_16x16x32_bf16 v[34:37], v[178:181], v[194:197], v[34:37]
	v_mfma_f32_16x16x32_bf16 v[22:25], v[170:173], v[204:207], v[22:25]
	v_mfma_f32_16x16x32_bf16 v[18:21], v[178:181], v[204:207], v[18:21]
	v_mfma_f32_16x16x32_bf16 v[6:9], v[170:173], v[212:215], v[6:9]
	v_mfma_f32_16x16x32_bf16 v[2:5], v[178:181], v[212:215], v[2:5]
	v_mfma_f32_16x16x32_bf16 v[54:57], v[174:177], v[190:193], v[54:57]
	v_mfma_f32_16x16x32_bf16 v[50:53], v[182:185], v[190:193], v[50:53]
	v_mfma_f32_16x16x32_bf16 v[38:41], v[174:177], v[200:203], v[38:41]
	v_mfma_f32_16x16x32_bf16 v[34:37], v[182:185], v[200:203], v[34:37]
	v_mfma_f32_16x16x32_bf16 v[22:25], v[174:177], v[208:211], v[22:25]
	v_mfma_f32_16x16x32_bf16 v[18:21], v[182:185], v[208:211], v[18:21]
	v_mfma_f32_16x16x32_bf16 v[6:9], v[174:177], v[216:219], v[6:9]
	v_mfma_f32_16x16x32_bf16 v[2:5], v[182:185], v[216:219], v[2:5]
	s_barrier
	s_setprio 0
	s_add_i32 s55, s55, 2
	s_add_u32 s30, s30, 0x100
	s_addc_u32 s31, s31, 0
	s_add_u32 s53, s53, 0x100
	s_addc_u32 s54, s54, 0
	s_cmp_gt_u32 s55, 61
	.p2align 8

; #define PG8_STAGE(bufoff, gbase, voff) do { _Pragma("unroll") for (int _i = 0; _i < 2; ++_i) \
;         __builtin_amdgcn_global_load_lds((const unsigned*)((const char*)(gbase) + (voff)[_i]), (PG8_LAS unsigned*)(lds + (bufoff) + ldsw + _i * 8192), 16, 0, 0); } while (0)
; #define PG8_LDA(dst, b, h) do { _Pragma("unroll") for (int m = 0; m < 4; ++m) _Pragma("unroll") for (int k = 0; k < 2; ++k) dst[m][k] = *(const PG8_LAS bf16x8*)(lds + PG8_SA(b, h) + aoff + m * 2048 + k * 1024); } while (0)
; #define PG8_LDB(dst, b, h) do { _Pragma("unroll") for (int n = 0; n < 2; ++n) _Pragma("unroll") for (int k = 0; k < 2; ++k) dst[n][k] = *(const PG8_LAS bf16x8*)(lds + PG8_SB(b, h) + boff + n * 2048 + k * 1024); } while (0)
; #define PG8_MMA(ai, bj, At, Bt) do { __builtin_amdgcn_s_setprio(1); _Pragma("unroll") for (int m = 0; m < 4; ++m) _Pragma("unroll") for (int n = 0; n < 2; ++n) _Pragma("unroll") for (int k = 0; k < 2; ++k) \
;         acc[ai][bj][m][n] = __builtin_amdgcn_mfma_f32_16x16x32_bf16(Bt[n][k], At[m][k], acc[ai][bj][m][n], 0, 0, 0); __builtin_amdgcn_s_setprio(0); } while (0)
; #define PG8_WAIT_V(n) asm volatile("s_waitcnt vmcnt(" #n ")" ::: "memory")
; #define PG8_BAR __builtin_amdgcn_s_barrier()
; template <class Epi, class Sched, bool ALIGN_EPI = false, bool SP2 = false>
; __device__ __forceinline__ void gemm_phase(PG8_LAS unsigned char* lds, const Gemm g, const Sched& S, const Epi& E) {
;     ...
;         for (int t = 0; t < nt; t += 2) {
;             const bool last = (t == nt - 2);
;             const char* a1 = cA + (size_t)(t + 1) * kstep;
;             const char* a2 = last ? nA : cA + (size_t)(t + 2) * kstep; const char* b2 = last ? nB : cB + (size_t)(t + 2) * kstep;
;             const char* a3 = a2 + kstep; const char* b3 = b2 + kstep;
;             if (last && has_next) S.a_ready(nxt);
;             if constexpr (SP2) {
;             PG8_LDB(B0, 0, 0); PG8_LDB(B1, 0, 1); PG8_SCHED; PG8_LDA(At, 0, 0); PG8_STAGE(PG8_SA(1, 1), a1 + hstep, voffA);
;             PG8_WAIT_V(8); PG8_WAIT_L(0); PG8_BAR; PG8_MMA(0, 0, At, B0); PG8_MMA(0, 1, At, B1); PG8_BAR; PG8_SCHED;
;             PG8_LDA(At, 0, 1); PG8_STAGE(PG8_SB(0, 0), b2, voffB); PG8_STAGE(PG8_SB(0, 1), b2 + hstep, voffB); PG8_STAGE(PG8_SA(0, 0), a2, voffA);
;             PG8_WAIT_V(8); PG8_WAIT_L(0); PG8_BAR; PG8_MMA(1, 0, At, B0); PG8_MMA(1, 1, At, B1); PG8_BAR; PG8_SCHED;
.LBB0_1163:
	s_add_u32 s14, s14, 0x2b0080
	s_addc_u32 s15, s15, 0
	s_add_u32 s39, s16, 0x100
	s_addc_u32 s40, s17, 0
	s_mov_b32 s41, -2
	s_waitcnt vmcnt(0)
	s_add_u32 s16, s14, 0xffd50000
	s_addc_u32 s17, s15, -1
	s_mov_b32 m0, s29
	s_nop 0
	global_load_lds_dwordx4 v128, s[16:17]
	s_mov_b32 m0, s30
	s_nop 0
	global_load_lds_dwordx4 v130, s[16:17]
	s_add_u32 s16, s16, 0x80
	s_addc_u32 s17, s17, 0
	ds_read_b128 v[140:143], v193
	ds_read_b128 v[144:147], v193 offset:1024
	ds_read_b128 v[148:151], v193 offset:2048
	ds_read_b128 v[152:155], v193 offset:3072
	ds_read_b128 v[156:159], v194
	ds_read_b128 v[160:163], v194 offset:1024
	ds_read_b128 v[164:167], v194 offset:2048
	ds_read_b128 v[168:171], v194 offset:3072
	s_cmpk_eq_i32 s41, 0xa8
	s_cselect_b32 s21, s5, s17
	s_cselect_b32 s20, s4, s16
	s_cselect_b32 s17, s13, s40
	s_cselect_b32 s16, s12, s39
	s_add_i32 m0, s24, 0xc000
	ds_read_b128 v[172:175], v195
	ds_read_b128 v[176:179], v195 offset:1024
	ds_read_b128 v[180:183], v195 offset:2048
	ds_read_b128 v[184:187], v195 offset:3072
	ds_read_b128 v[196:199], v195 offset:4096
	ds_read_b128 v[200:203], v195 offset:5120
	ds_read_b128 v[204:207], v195 offset:6144
	ds_read_b128 v[208:211], v195 offset:7168
	global_load_lds_dwordx4 v132, s[14:15]
	s_add_i32 m0, s24, 0xe000
	s_nop 0
	global_load_lds_dwordx4 v134, s[14:15]
	s_waitcnt vmcnt(8)
	s_waitcnt lgkmcnt(0)
	s_setprio 1
	s_barrier
	v_mfma_f32_16x16x32_bf16 v[124:127], v[140:143], v[172:175], 0
	v_mfma_f32_16x16x32_bf16 v[120:123], v[148:151], v[172:175], 0
	v_mfma_f32_16x16x32_bf16 v[112:115], v[140:143], v[180:183], 0
	v_mfma_f32_16x16x32_bf16 v[104:107], v[148:151], v[180:183], 0
	v_mfma_f32_16x16x32_bf16 v[96:99], v[140:143], v[196:199], 0
	v_mfma_f32_16x16x32_bf16 v[88:91], v[148:151], v[196:199], 0
	v_mfma_f32_16x16x32_bf16 v[80:83], v[140:143], v[204:207], 0
	v_mfma_f32_16x16x32_bf16 v[72:75], v[148:151], v[204:207], 0
	v_mfma_f32_16x16x32_bf16 v[124:127], v[144:147], v[176:179], v[124:127]
	v_mfma_f32_16x16x32_bf16 v[120:123], v[152:155], v[176:179], v[120:123]
	v_mfma_f32_16x16x32_bf16 v[112:115], v[144:147], v[184:187], v[112:115]
	v_mfma_f32_16x16x32_bf16 v[104:107], v[152:155], v[184:187], v[104:107]
	v_mfma_f32_16x16x32_bf16 v[96:99], v[144:147], v[200:203], v[96:99]
	v_mfma_f32_16x16x32_bf16 v[88:91], v[152:155], v[200:203], v[88:91]
	v_mfma_f32_16x16x32_bf16 v[80:83], v[144:147], v[208:211], v[80:83]
	v_mfma_f32_16x16x32_bf16 v[72:75], v[152:155], v[208:211], v[72:75]
	v_mfma_f32_16x16x32_bf16 v[116:119], v[156:159], v[172:175], 0
	v_mfma_f32_16x16x32_bf16 v[108:111], v[164:167], v[172:175], 0
	v_mfma_f32_16x16x32_bf16 v[100:103], v[156:159], v[180:183], 0
	v_mfma_f32_16x16x32_bf16 v[92:95], v[164:167], v[180:183], 0
	v_mfma_f32_16x16x32_bf16 v[84:87], v[156:159], v[196:199], 0
	v_mfma_f32_16x16x32_bf16 v[76:79], v[164:167], v[196:199], 0
	v_mfma_f32_16x16x32_bf16 v[68:71], v[156:159], v[204:207], 0
	v_mfma_f32_16x16x32_bf16 v[64:67], v[164:167], v[204:207], 0
	v_mfma_f32_16x16x32_bf16 v[116:119], v[160:163], v[176:179], v[116:119]
	v_mfma_f32_16x16x32_bf16 v[108:111], v[168:171], v[176:179], v[108:111]
	v_mfma_f32_16x16x32_bf16 v[100:103], v[160:163], v[184:187], v[100:103]
	v_mfma_f32_16x16x32_bf16 v[92:95], v[168:171], v[184:187], v[92:95]
	v_mfma_f32_16x16x32_bf16 v[84:87], v[160:163], v[200:203], v[84:87]
	v_mfma_f32_16x16x32_bf16 v[76:79], v[168:171], v[200:203], v[76:79]
	v_mfma_f32_16x16x32_bf16 v[68:71], v[160:163], v[208:211], v[68:71]
	v_mfma_f32_16x16x32_bf16 v[64:67], v[168:171], v[208:211], v[64:67]
	s_barrier
	s_setprio 0
	s_add_i32 s42, s33, s23
	s_mov_b32 m0, s42
	ds_read_b128 v[172:175], v195 offset:16384
	ds_read_b128 v[176:179], v195 offset:17408
	ds_read_b128 v[180:183], v195 offset:18432
	ds_read_b128 v[184:187], v195 offset:19456
	ds_read_b128 v[196:199], v195 offset:20480
	ds_read_b128 v[200:203], v195 offset:21504
	ds_read_b128 v[204:207], v195 offset:22528
	ds_read_b128 v[208:211], v195 offset:23552
	global_load_lds_dwordx4 v128, s[16:17]
	s_add_i32 m0, s42, 0x2000
	s_add_u32 s42, s16, 0x2b0000
	s_addc_u32 s43, s17, 0
	s_add_i32 s44, s34, s23
	global_load_lds_dwordx4 v130, s[16:17]
	s_mov_b32 m0, s44
	s_nop 0
	global_load_lds_dwordx4 v128, s[42:43]
	s_add_i32 m0, s44, 0x2000
	s_nop 0
	global_load_lds_dwordx4 v130, s[42:43]
	s_waitcnt vmcnt(6)
	s_waitcnt lgkmcnt(0)
	s_setprio 1
	s_barrier
	v_mfma_f32_16x16x32_bf16 v[60:63], v[140:143], v[172:175], 0
	v_mfma_f32_16x16x32_bf16 v[56:59], v[148:151], v[172:175], 0
	v_mfma_f32_16x16x32_bf16 v[48:51], v[140:143], v[180:183], 0
	v_mfma_f32_16x16x32_bf16 v[40:43], v[148:151], v[180:183], 0
	v_mfma_f32_16x16x32_bf16 v[32:35], v[140:143], v[196:199], 0
	v_mfma_f32_16x16x32_bf16 v[24:27], v[148:151], v[196:199], 0
	v_mfma_f32_16x16x32_bf16 v[16:19], v[140:143], v[204:207], 0
	v_mfma_f32_16x16x32_bf16 v[8:11], v[148:151], v[204:207], 0
	v_mfma_f32_16x16x32_bf16 v[60:63], v[144:147], v[176:179], v[60:63]
	v_mfma_f32_16x16x32_bf16 v[56:59], v[152:155], v[176:179], v[56:59]
	v_mfma_f32_16x16x32_bf16 v[48:51], v[144:147], v[184:187], v[48:51]
	v_mfma_f32_16x16x32_bf16 v[40:43], v[152:155], v[184:187], v[40:43]
	v_mfma_f32_16x16x32_bf16 v[32:35], v[144:147], v[200:203], v[32:35]
	v_mfma_f32_16x16x32_bf16 v[24:27], v[152:155], v[200:203], v[24:27]
	v_mfma_f32_16x16x32_bf16 v[16:19], v[144:147], v[208:211], v[16:19]
	v_mfma_f32_16x16x32_bf16 v[8:11], v[152:155], v[208:211], v[8:11]
	v_mfma_f32_16x16x32_bf16 v[52:55], v[156:159], v[172:175], 0
	v_mfma_f32_16x16x32_bf16 v[44:47], v[164:167], v[172:175], 0
	v_mfma_f32_16x16x32_bf16 v[36:39], v[156:159], v[180:183], 0
	v_mfma_f32_16x16x32_bf16 v[28:31], v[164:167], v[180:183], 0
	v_mfma_f32_16x16x32_bf16 v[20:23], v[156:159], v[196:199], 0
	v_mfma_f32_16x16x32_bf16 v[12:15], v[164:167], v[196:199], 0
	v_mfma_f32_16x16x32_bf16 v[4:7], v[156:159], v[204:207], 0
	v_mfma_f32_16x16x32_bf16 v[0:3], v[164:167], v[204:207], 0
	v_mfma_f32_16x16x32_bf16 v[52:55], v[160:163], v[176:179], v[52:55]
	v_mfma_f32_16x16x32_bf16 v[44:47], v[168:171], v[176:179], v[44:47]
	v_mfma_f32_16x16x32_bf16 v[36:39], v[160:163], v[184:187], v[36:39]
	v_mfma_f32_16x16x32_bf16 v[28:31], v[168:171], v[184:187], v[28:31]
	v_mfma_f32_16x16x32_bf16 v[20:23], v[160:163], v[200:203], v[20:23]
	v_mfma_f32_16x16x32_bf16 v[12:15], v[168:171], v[200:203], v[12:15]
	v_mfma_f32_16x16x32_bf16 v[4:7], v[160:163], v[208:211], v[4:7]
	v_mfma_f32_16x16x32_bf16 v[0:3], v[168:171], v[208:211], v[0:3]
	s_barrier
; #define PG8_STAGE(bufoff, gbase, voff) do { _Pragma("unroll") for (int _i = 0; _i < 2; ++_i) \
;         __builtin_amdgcn_global_load_lds((const unsigned*)((const char*)(gbase) + (voff)[_i]), (PG8_LAS unsigned*)(lds + (bufoff) + ldsw + _i * 8192), 16, 0, 0); } while (0)
; #define PG8_LDA(dst, b, h) do { _Pragma("unroll") for (int m = 0; m < 4; ++m) _Pragma("unroll") for (int k = 0; k < 2; ++k) dst[m][k] = *(const PG8_LAS bf16x8*)(lds + PG8_SA(b, h) + aoff + m * 2048 + k * 1024); } while (0)
; #define PG8_LDB(dst, b, h) do { _Pragma("unroll") for (int n = 0; n < 2; ++n) _Pragma("unroll") for (int k = 0; k < 2; ++k) dst[n][k] = *(const PG8_LAS bf16x8*)(lds + PG8_SB(b, h) + boff + n * 2048 + k * 1024); } while (0)
; #define PG8_MMA(ai, bj, At, Bt) do { __builtin_amdgcn_s_setprio(1); _Pragma("unroll") for (int m = 0; m < 4; ++m) _Pragma("unroll") for (int n = 0; n < 2; ++n) _Pragma("unroll") for (int k = 0; k < 2; ++k) \
;         acc[ai][bj][m][n] = __builtin_amdgcn_mfma_f32_16x16x32_bf16(Bt[n][k], At[m][k], acc[ai][bj][m][n], 0, 0, 0); __builtin_amdgcn_s_setprio(0); } while (0)
; #define PG8_WAIT_V(n) asm volatile("s_waitcnt vmcnt(" #n ")" ::: "memory")
; #define PG8_WAIT_L(n) asm volatile("s_waitcnt lgkmcnt(" #n ")" ::: "memory")
; #define PG8_BAR __builtin_amdgcn_s_barrier()
; #define PG8_SCHED __builtin_amdgcn_sched_barrier(0)
; template <class Epi, class Sched, bool ALIGN_EPI = false, bool SP2 = false>
; __device__ __forceinline__ void gemm_phase(PG8_LAS unsigned char* lds, const Gemm g, const Sched& S, const Epi& E) {
;     ...
;             PG8_LDB(B0, 1, 0); PG8_LDB(B1, 1, 1); PG8_SCHED; PG8_LDA(At, 1, 0); PG8_STAGE(PG8_SA(0, 1), a2 + hstep, voffA);
;             PG8_WAIT_V(8); PG8_WAIT_L(0); PG8_BAR; PG8_MMA(0, 0, At, B0); PG8_MMA(0, 1, At, B1); PG8_BAR; PG8_SCHED;
;             PG8_LDA(At, 1, 1); PG8_STAGE(PG8_SB(1, 0), b3, voffB); PG8_STAGE(PG8_SB(1, 1), b3 + hstep, voffB); PG8_STAGE(PG8_SA(1, 0), a3, voffA);
;             PG8_WAIT_V(8); PG8_WAIT_L(0); PG8_BAR; PG8_MMA(1, 0, At, B0); PG8_MMA(1, 1, At, B1); PG8_BAR; PG8_SCHED;
	s_setprio 0
	s_mov_b32 m0, s24
	s_nop 0
	global_load_lds_dwordx4 v128, s[20:21]
	s_mov_b32 m0, s25
	s_nop 0
	global_load_lds_dwordx4 v130, s[20:21]
	s_add_i32 s42, 0, 0x18000
	s_add_i32 s43, 0, 0x1c000
	v_add_u32_e32 v152, s42, v191
	v_add_u32_e32 v168, s43, v191
	ds_read_b128 v[140:143], v152
	ds_read_b128 v[144:147], v152 offset:1024
	ds_read_b128 v[148:151], v152 offset:2048
	ds_read_b128 v[152:155], v152 offset:3072
	ds_read_b128 v[156:159], v168
	ds_read_b128 v[160:163], v168 offset:1024
	ds_read_b128 v[164:167], v168 offset:2048
	ds_read_b128 v[168:171], v168 offset:3072
	s_add_u32 s20, s20, 0x2b0000
	s_addc_u32 s21, s21, 0
	s_mov_b32 m0, s26
	ds_read_b128 v[172:175], v195 offset:32768
	ds_read_b128 v[176:179], v195 offset:33792
	ds_read_b128 v[180:183], v195 offset:34816
	ds_read_b128 v[184:187], v195 offset:35840
	ds_read_b128 v[196:199], v195 offset:36864
	ds_read_b128 v[200:203], v195 offset:37888
	ds_read_b128 v[204:207], v195 offset:38912
	ds_read_b128 v[208:211], v195 offset:39936
	global_load_lds_dwordx4 v128, s[20:21]
	s_mov_b32 m0, s27
	s_nop 0
	global_load_lds_dwordx4 v130, s[20:21]
	s_waitcnt vmcnt(8)
	s_waitcnt lgkmcnt(0)
	s_setprio 1
	s_barrier
	v_mfma_f32_16x16x32_bf16 v[124:127], v[140:143], v[172:175], v[124:127]
	v_mfma_f32_16x16x32_bf16 v[120:123], v[148:151], v[172:175], v[120:123]
	v_mfma_f32_16x16x32_bf16 v[112:115], v[140:143], v[180:183], v[112:115]
	v_mfma_f32_16x16x32_bf16 v[104:107], v[148:151], v[180:183], v[104:107]
	v_mfma_f32_16x16x32_bf16 v[96:99], v[140:143], v[196:199], v[96:99]
	v_mfma_f32_16x16x32_bf16 v[88:91], v[148:151], v[196:199], v[88:91]
	v_mfma_f32_16x16x32_bf16 v[80:83], v[140:143], v[204:207], v[80:83]
	v_mfma_f32_16x16x32_bf16 v[72:75], v[148:151], v[204:207], v[72:75]
	v_mfma_f32_16x16x32_bf16 v[124:127], v[144:147], v[176:179], v[124:127]
	v_mfma_f32_16x16x32_bf16 v[120:123], v[152:155], v[176:179], v[120:123]
	v_mfma_f32_16x16x32_bf16 v[112:115], v[144:147], v[184:187], v[112:115]
	v_mfma_f32_16x16x32_bf16 v[104:107], v[152:155], v[184:187], v[104:107]
	v_mfma_f32_16x16x32_bf16 v[96:99], v[144:147], v[200:203], v[96:99]
	v_mfma_f32_16x16x32_bf16 v[88:91], v[152:155], v[200:203], v[88:91]
	v_mfma_f32_16x16x32_bf16 v[80:83], v[144:147], v[208:211], v[80:83]
	v_mfma_f32_16x16x32_bf16 v[72:75], v[152:155], v[208:211], v[72:75]
	v_mfma_f32_16x16x32_bf16 v[116:119], v[156:159], v[172:175], v[116:119]
	v_mfma_f32_16x16x32_bf16 v[108:111], v[164:167], v[172:175], v[108:111]
	v_mfma_f32_16x16x32_bf16 v[100:103], v[156:159], v[180:183], v[100:103]
	v_mfma_f32_16x16x32_bf16 v[92:95], v[164:167], v[180:183], v[92:95]
	v_mfma_f32_16x16x32_bf16 v[84:87], v[156:159], v[196:199], v[84:87]
	v_mfma_f32_16x16x32_bf16 v[76:79], v[164:167], v[196:199], v[76:79]
	v_mfma_f32_16x16x32_bf16 v[68:71], v[156:159], v[204:207], v[68:71]
	v_mfma_f32_16x16x32_bf16 v[64:67], v[164:167], v[204:207], v[64:67]
	v_mfma_f32_16x16x32_bf16 v[116:119], v[160:163], v[176:179], v[116:119]
	v_mfma_f32_16x16x32_bf16 v[108:111], v[168:171], v[176:179], v[108:111]
	v_mfma_f32_16x16x32_bf16 v[100:103], v[160:163], v[184:187], v[100:103]
	v_mfma_f32_16x16x32_bf16 v[92:95], v[168:171], v[184:187], v[92:95]
	v_mfma_f32_16x16x32_bf16 v[84:87], v[160:163], v[200:203], v[84:87]
	v_mfma_f32_16x16x32_bf16 v[76:79], v[168:171], v[200:203], v[76:79]
	v_mfma_f32_16x16x32_bf16 v[68:71], v[160:163], v[208:211], v[68:71]
	v_mfma_f32_16x16x32_bf16 v[64:67], v[168:171], v[208:211], v[64:67]
	s_barrier
	s_setprio 0
	s_add_i32 s20, s42, s23
	s_add_u32 s16, s16, 0x80
	s_addc_u32 s17, s17, 0
	s_mov_b32 m0, s20
	ds_read_b128 v[172:175], v195 offset:49152
	ds_read_b128 v[176:179], v195 offset:50176
	ds_read_b128 v[180:183], v195 offset:51200
	ds_read_b128 v[184:187], v195 offset:52224
	ds_read_b128 v[196:199], v195 offset:53248
	ds_read_b128 v[200:203], v195 offset:54272
	ds_read_b128 v[204:207], v195 offset:55296
	ds_read_b128 v[208:211], v195 offset:56320
	global_load_lds_dwordx4 v128, s[16:17]
	s_add_i32 m0, s20, 0x2000
	s_add_i32 s20, s43, s23
	global_load_lds_dwordx4 v130, s[16:17]
	s_add_u32 s16, s16, 0x2b0000
	s_addc_u32 s17, s17, 0
	s_mov_b32 m0, s20
	s_nop 0
	global_load_lds_dwordx4 v128, s[16:17]
	s_add_i32 m0, s20, 0x2000
	s_nop 0
	global_load_lds_dwordx4 v130, s[16:17]
	s_waitcnt vmcnt(6)
	s_waitcnt lgkmcnt(0)
	s_setprio 1
	s_barrier
	v_mfma_f32_16x16x32_bf16 v[60:63], v[140:143], v[172:175], v[60:63]
	v_mfma_f32_16x16x32_bf16 v[56:59], v[148:151], v[172:175], v[56:59]
	v_mfma_f32_16x16x32_bf16 v[48:51], v[140:143], v[180:183], v[48:51]
	v_mfma_f32_16x16x32_bf16 v[40:43], v[148:151], v[180:183], v[40:43]
	v_mfma_f32_16x16x32_bf16 v[32:35], v[140:143], v[196:199], v[32:35]
	v_mfma_f32_16x16x32_bf16 v[24:27], v[148:151], v[196:199], v[24:27]
	v_mfma_f32_16x16x32_bf16 v[16:19], v[140:143], v[204:207], v[16:19]
	v_mfma_f32_16x16x32_bf16 v[8:11], v[148:151], v[204:207], v[8:11]
	v_mfma_f32_16x16x32_bf16 v[60:63], v[144:147], v[176:179], v[60:63]
	v_mfma_f32_16x16x32_bf16 v[56:59], v[152:155], v[176:179], v[56:59]
	v_mfma_f32_16x16x32_bf16 v[48:51], v[144:147], v[184:187], v[48:51]
	v_mfma_f32_16x16x32_bf16 v[40:43], v[152:155], v[184:187], v[40:43]
	v_mfma_f32_16x16x32_bf16 v[32:35], v[144:147], v[200:203], v[32:35]
	v_mfma_f32_16x16x32_bf16 v[24:27], v[152:155], v[200:203], v[24:27]
	v_mfma_f32_16x16x32_bf16 v[16:19], v[144:147], v[208:211], v[16:19]
	v_mfma_f32_16x16x32_bf16 v[8:11], v[152:155], v[208:211], v[8:11]
	v_mfma_f32_16x16x32_bf16 v[52:55], v[156:159], v[172:175], v[52:55]
	v_mfma_f32_16x16x32_bf16 v[44:47], v[164:167], v[172:175], v[44:47]
	v_mfma_f32_16x16x32_bf16 v[36:39], v[156:159], v[180:183], v[36:39]
	v_mfma_f32_16x16x32_bf16 v[28:31], v[164:167], v[180:183], v[28:31]
	v_mfma_f32_16x16x32_bf16 v[20:23], v[156:159], v[196:199], v[20:23]
	v_mfma_f32_16x16x32_bf16 v[12:15], v[164:167], v[196:199], v[12:15]
	v_mfma_f32_16x16x32_bf16 v[4:7], v[156:159], v[204:207], v[4:7]
	v_mfma_f32_16x16x32_bf16 v[0:3], v[164:167], v[204:207], v[0:3]
	v_mfma_f32_16x16x32_bf16 v[52:55], v[160:163], v[176:179], v[52:55]
	v_mfma_f32_16x16x32_bf16 v[44:47], v[168:171], v[176:179], v[44:47]
	v_mfma_f32_16x16x32_bf16 v[36:39], v[160:163], v[184:187], v[36:39]
	v_mfma_f32_16x16x32_bf16 v[28:31], v[168:171], v[184:187], v[28:31]
	v_mfma_f32_16x16x32_bf16 v[20:23], v[160:163], v[200:203], v[20:23]
	v_mfma_f32_16x16x32_bf16 v[12:15], v[168:171], v[200:203], v[12:15]
	v_mfma_f32_16x16x32_bf16 v[4:7], v[160:163], v[208:211], v[4:7]
	v_mfma_f32_16x16x32_bf16 v[0:3], v[168:171], v[208:211], v[0:3]
	s_barrier
	s_setprio 0
	s_add_i32 s41, s41, 2
	s_add_u32 s14, s14, 0x100
	s_addc_u32 s15, s15, 0
	s_add_u32 s39, s39, 0x100
	s_addc_u32 s40, s40, 0
	s_cmpk_gt_u32 s41, 0xa9
	.p2align 8
